# P5: state-row outputs fused into the pool/conv row loops, the four copy loops skipped
# baseline (speedup 1.0000x reference)
.LBB0_801:
	s_add_u32 s16, s34, 0x2b500000
	s_addc_u32 s17, s35, 0
	s_cmp_lt_i32 s20, 6
	s_cselect_b64 s[0:1], -1, 0
	s_cmp_gt_i32 s21, 5
	s_cselect_b64 s[2:3], -1, 0
	s_and_b64 s[0:1], s[0:1], s[2:3]
	v_readlane_b32 s76, v254, 37
	v_readlane_b32 s68, v254, 41
	s_andn2_b64 vcc, exec, s[0:1]
	v_readlane_b32 s77, v254, 38
	v_readlane_b32 s69, v254, 42
	s_cbranch_vccnz .LBB0_940
	v_readlane_b32 s0, v255, 2
	s_waitcnt vmcnt(31)
	v_mbcnt_lo_u32_b32 v0, -1, 0
	v_mbcnt_hi_u32_b32 v0, -1, v0
	s_waitcnt vmcnt(24)
	v_or_b32_e32 v28, s0, v0
	v_readlane_b32 s0, v254, 15
	s_waitcnt vmcnt(16)
	s_nop 0
	v_lshl_add_u32 v62, s0, 9, v28
	v_mbcnt_lo_u32_b32 v0, -1, 0
	v_mbcnt_hi_u32_b32 v0, -1, v0
	s_add_u32 s54, s34, 0x47c00000
	s_addc_u32 s55, s35, 0
	v_readlane_b32 s86, v254, 5
	v_readlane_b32 s87, v254, 6
	v_readlane_b32 s0, v254, 15
	v_readlane_b32 s46, v255, 2
	s_nop 3
	s_lshl_b32 s0, s0, 9
	s_or_b32 s0, s0, s46
	s_add_u32 s56, s34, 0x2b500000
	s_addc_u32 s57, s35, 0
.Lp5_pool_outer:
	s_cmp_ge_u32 s0, 0x16800
	s_cbranch_scc1 .Lp5_pool_exit
	s_cmp_ge_u32 s0, 0x15800
	s_cbranch_scc1 .Lp5_pool_sample
	s_lshr_b32 s58, s0, 8
	s_and_b32 s60, s0, 0xff
	s_cmp_ge_u32 s58, 86
	s_cselect_b32 s59, 1, 0
	s_cmp_ge_u32 s58, 172
	s_cselect_b32 s46, 1, 0
	s_add_u32 s59, s59, s46
	s_cmp_ge_u32 s58, 258
	s_cselect_b32 s46, 1, 0
	s_add_u32 s59, s59, s46
	s_mul_i32 s46, s59, 86
	s_sub_u32 s58, s58, s46
	s_mul_i32 s1, s58, 24
	s_movk_i32 s2, 24
	s_mul_i32 s3, s59, 0x810
	s_mov_b32 s8, 1
	s_mov_b32 s9, 0
	s_mov_b64 s[52:53], 0
	s_mul_i32 s46, s59, 0x1e000
	s_add_u32 s46, s46, 0x8400000
	s_sub_i32 s82, s1, 2049
	s_branch .Lp5_pool_item
.Lp5_pool_sample:
	s_sub_u32 s46, s0, 0x15800
	s_and_b32 s60, s46, 0xff
	s_lshr_b32 s58, s46, 8
	s_lshr_b32 s59, s58, 1
	s_and_b32 s1, s58, 1
	s_lshl_b32 s1, s1, 4
	s_movk_i32 s2, 16
	s_lshl_b32 s3, s59, 5
	s_add_u32 s3, s3, 0x2040
	s_mov_b32 s8, 16
	s_mov_b32 s9, 1
	v_readlane_b32 s52, v255, 11
	v_readlane_b32 s53, v255, 12
	s_mul_i32 s46, s59, 0x1e000
	s_nop 1
	s_add_u32 s52, s52, s46
	s_addc_u32 s53, s53, 0
	s_add_u32 s46, s46, 0x84b8000
	s_sub_i32 s82, s1, 17
.Lp5_pool_item:
	s_lshl_b32 s47, s82, 13
	s_add_i32 s46, s46, s47
	s_ashr_i32 s47, s46, 31
	s_add_u32 s78, s86, s46
	s_addc_u32 s79, s87, s47
	s_lshr_b32 s46, s60, 6
	s_lshl_b32 s6, 2, s46
	s_sub_u32 s7, s6, 1
	s_lshl_b32 s46, s46, 23
	s_sub_u32 s10, 0x3f000000, s46
	v_add_u32_e32 v1, s60, v0
	v_lshlrev_b32_e32 v2, 5, v1
	v_lshlrev_b32_e32 v1, 4, v1
	v_mov_b32_e32 v16, 0
	v_mov_b32_e32 v17, 0
	v_mov_b32_e32 v18, 0
	v_mov_b32_e32 v19, 0
	v_mov_b32_e32 v20, 0
	v_mov_b32_e32 v21, 0
	v_mov_b32_e32 v22, 0
	v_mov_b32_e32 v23, 0
	s_mov_b32 s32, s1
	s_mov_b32 s61, 0
	s_add_u32 s46, s3, s1
	s_lshl_b32 s46, s46, 12
	s_add_u32 s42, s56, s46
	s_addc_u32 s43, s57, 0

.Lp5_pool_inv_0:
	v_lshlrev_b32_e32 v24, 16, v64
	v_and_b32_e32 v25, 0xffff0000, v64
	v_lshlrev_b32_e32 v26, 16, v65
	v_and_b32_e32 v27, 0xffff0000, v65
	v_lshlrev_b32_e32 v28, 16, v66
	v_and_b32_e32 v29, 0xffff0000, v66
	v_lshlrev_b32_e32 v30, 16, v67
	v_and_b32_e32 v31, 0xffff0000, v67
	s_cmp_lt_i32 s82, 0
	s_cbranch_scc1 .Lp5_pool_nost_0
	global_store_dwordx4 v2, v[24:27], s[78:79]
	global_store_dwordx4 v2, v[28:31], s[78:79] offset:16
.Lp5_pool_nost_0:
	v_pk_add_f32 v[16:17], v[16:17], v[24:25]
	v_pk_add_f32 v[18:19], v[18:19], v[26:27]
	v_pk_add_f32 v[20:21], v[20:21], v[28:29]
	v_pk_add_f32 v[22:23], v[22:23], v[30:31]
	v_fma_f32 v32, v16, v3, -v24
	v_fma_f32 v33, v17, v3, -v25
	v_fma_f32 v34, v18, v3, -v26
	v_fma_f32 v35, v19, v3, -v27
	v_fma_f32 v36, v20, v3, -v28
	v_fma_f32 v37, v21, v3, -v29
	v_fma_f32 v38, v22, v3, -v30
	v_fma_f32 v39, v23, v3, -v31
	v_cvt_pk_bf16_f32 v40, v32, v33
	v_cvt_pk_bf16_f32 v41, v34, v35
	v_cvt_pk_bf16_f32 v42, v36, v37
	v_cvt_pk_bf16_f32 v43, v38, v39
	global_store_dwordx4 v1, v[40:43], s[42:43]
	v_pk_add_f32 v[16:17], v[16:17], v[128:129] neg_lo:[0,1] neg_hi:[0,1]
	v_pk_add_f32 v[18:19], v[18:19], v[130:131] neg_lo:[0,1] neg_hi:[0,1]
	v_pk_add_f32 v[20:21], v[20:21], v[132:133] neg_lo:[0,1] neg_hi:[0,1]
	v_pk_add_f32 v[22:23], v[22:23], v[134:135] neg_lo:[0,1] neg_hi:[0,1]
	s_add_u32 s42, s42, 0x1000
	s_addc_u32 s43, s43, 0
	s_add_u32 s78, s78, 0x2000
	s_addc_u32 s79, s79, 0
	s_add_i32 s82, s82, 1
	s_add_u32 s32, s32, 1
	s_sub_u32 s2, s2, 1
	s_cmp_eq_u32 s2, 0
	s_cbranch_scc1 .Lp5_pool_next_item
	s_add_u32 s67, s8, s32
	s_cmp_lt_u32 s67, s6
	s_cbranch_scc1 .Lp5_pool_div_1
	v_mov_b32_e32 v3, s10
	s_branch .Lp5_pool_inv_1

.Lp5_pool_inv_1:
	v_lshlrev_b32_e32 v24, 16, v68
	v_and_b32_e32 v25, 0xffff0000, v68
	v_lshlrev_b32_e32 v26, 16, v69
	v_and_b32_e32 v27, 0xffff0000, v69
	v_lshlrev_b32_e32 v28, 16, v70
	v_and_b32_e32 v29, 0xffff0000, v70
	v_lshlrev_b32_e32 v30, 16, v71
	v_and_b32_e32 v31, 0xffff0000, v71
	s_cmp_lt_i32 s82, 0
	s_cbranch_scc1 .Lp5_pool_nost_1
	global_store_dwordx4 v2, v[24:27], s[78:79]
	global_store_dwordx4 v2, v[28:31], s[78:79] offset:16
.Lp5_pool_nost_1:
	v_pk_add_f32 v[16:17], v[16:17], v[24:25]
	v_pk_add_f32 v[18:19], v[18:19], v[26:27]
	v_pk_add_f32 v[20:21], v[20:21], v[28:29]
	v_pk_add_f32 v[22:23], v[22:23], v[30:31]
	v_fma_f32 v32, v16, v3, -v24
	v_fma_f32 v33, v17, v3, -v25
	v_fma_f32 v34, v18, v3, -v26
	v_fma_f32 v35, v19, v3, -v27
	v_fma_f32 v36, v20, v3, -v28
	v_fma_f32 v37, v21, v3, -v29
	v_fma_f32 v38, v22, v3, -v30
	v_fma_f32 v39, v23, v3, -v31
	v_cvt_pk_bf16_f32 v44, v32, v33
	v_cvt_pk_bf16_f32 v45, v34, v35
	v_cvt_pk_bf16_f32 v46, v36, v37
	v_cvt_pk_bf16_f32 v47, v38, v39
	global_store_dwordx4 v1, v[44:47], s[42:43]
	v_pk_add_f32 v[16:17], v[16:17], v[136:137] neg_lo:[0,1] neg_hi:[0,1]
	v_pk_add_f32 v[18:19], v[18:19], v[138:139] neg_lo:[0,1] neg_hi:[0,1]
	v_pk_add_f32 v[20:21], v[20:21], v[140:141] neg_lo:[0,1] neg_hi:[0,1]
	v_pk_add_f32 v[22:23], v[22:23], v[142:143] neg_lo:[0,1] neg_hi:[0,1]
	s_add_u32 s42, s42, 0x1000
	s_addc_u32 s43, s43, 0
	s_add_u32 s78, s78, 0x2000
	s_addc_u32 s79, s79, 0
	s_add_i32 s82, s82, 1
	s_add_u32 s32, s32, 1
	s_sub_u32 s2, s2, 1
	s_cmp_eq_u32 s2, 0
	s_cbranch_scc1 .Lp5_pool_next_item
	s_add_u32 s67, s8, s32
	s_cmp_lt_u32 s67, s6
	s_cbranch_scc1 .Lp5_pool_div_2
	v_mov_b32_e32 v3, s10
	s_branch .Lp5_pool_inv_2

.Lp5_pool_inv_2:
	v_lshlrev_b32_e32 v24, 16, v72
	v_and_b32_e32 v25, 0xffff0000, v72
	v_lshlrev_b32_e32 v26, 16, v73
	v_and_b32_e32 v27, 0xffff0000, v73
	v_lshlrev_b32_e32 v28, 16, v74
	v_and_b32_e32 v29, 0xffff0000, v74
	v_lshlrev_b32_e32 v30, 16, v75
	v_and_b32_e32 v31, 0xffff0000, v75
	s_cmp_lt_i32 s82, 0
	s_cbranch_scc1 .Lp5_pool_nost_2
	global_store_dwordx4 v2, v[24:27], s[78:79]
	global_store_dwordx4 v2, v[28:31], s[78:79] offset:16
.Lp5_pool_nost_2:
	v_pk_add_f32 v[16:17], v[16:17], v[24:25]
	v_pk_add_f32 v[18:19], v[18:19], v[26:27]
	v_pk_add_f32 v[20:21], v[20:21], v[28:29]
	v_pk_add_f32 v[22:23], v[22:23], v[30:31]
	v_fma_f32 v32, v16, v3, -v24
	v_fma_f32 v33, v17, v3, -v25
	v_fma_f32 v34, v18, v3, -v26
	v_fma_f32 v35, v19, v3, -v27
	v_fma_f32 v36, v20, v3, -v28
	v_fma_f32 v37, v21, v3, -v29
	v_fma_f32 v38, v22, v3, -v30
	v_fma_f32 v39, v23, v3, -v31
	v_cvt_pk_bf16_f32 v40, v32, v33
	v_cvt_pk_bf16_f32 v41, v34, v35
	v_cvt_pk_bf16_f32 v42, v36, v37
	v_cvt_pk_bf16_f32 v43, v38, v39
	global_store_dwordx4 v1, v[40:43], s[42:43]
	v_pk_add_f32 v[16:17], v[16:17], v[144:145] neg_lo:[0,1] neg_hi:[0,1]
	v_pk_add_f32 v[18:19], v[18:19], v[146:147] neg_lo:[0,1] neg_hi:[0,1]
	v_pk_add_f32 v[20:21], v[20:21], v[148:149] neg_lo:[0,1] neg_hi:[0,1]
	v_pk_add_f32 v[22:23], v[22:23], v[150:151] neg_lo:[0,1] neg_hi:[0,1]
	s_add_u32 s42, s42, 0x1000
	s_addc_u32 s43, s43, 0
	s_add_u32 s78, s78, 0x2000
	s_addc_u32 s79, s79, 0
	s_add_i32 s82, s82, 1
	s_add_u32 s32, s32, 1
	s_sub_u32 s2, s2, 1
	s_cmp_eq_u32 s2, 0
	s_cbranch_scc1 .Lp5_pool_next_item
	s_add_u32 s67, s8, s32
	s_cmp_lt_u32 s67, s6
	s_cbranch_scc1 .Lp5_pool_div_3
	v_mov_b32_e32 v3, s10
	s_branch .Lp5_pool_inv_3

.Lp5_pool_inv_3:
	v_lshlrev_b32_e32 v24, 16, v76
	v_and_b32_e32 v25, 0xffff0000, v76
	v_lshlrev_b32_e32 v26, 16, v77
	v_and_b32_e32 v27, 0xffff0000, v77
	v_lshlrev_b32_e32 v28, 16, v78
	v_and_b32_e32 v29, 0xffff0000, v78
	v_lshlrev_b32_e32 v30, 16, v79
	v_and_b32_e32 v31, 0xffff0000, v79
	s_cmp_lt_i32 s82, 0
	s_cbranch_scc1 .Lp5_pool_nost_3
	global_store_dwordx4 v2, v[24:27], s[78:79]
	global_store_dwordx4 v2, v[28:31], s[78:79] offset:16
.Lp5_pool_nost_3:
	v_pk_add_f32 v[16:17], v[16:17], v[24:25]
	v_pk_add_f32 v[18:19], v[18:19], v[26:27]
	v_pk_add_f32 v[20:21], v[20:21], v[28:29]
	v_pk_add_f32 v[22:23], v[22:23], v[30:31]
	v_fma_f32 v32, v16, v3, -v24
	v_fma_f32 v33, v17, v3, -v25
	v_fma_f32 v34, v18, v3, -v26
	v_fma_f32 v35, v19, v3, -v27
	v_fma_f32 v36, v20, v3, -v28
	v_fma_f32 v37, v21, v3, -v29
	v_fma_f32 v38, v22, v3, -v30
	v_fma_f32 v39, v23, v3, -v31
	v_cvt_pk_bf16_f32 v44, v32, v33
	v_cvt_pk_bf16_f32 v45, v34, v35
	v_cvt_pk_bf16_f32 v46, v36, v37
	v_cvt_pk_bf16_f32 v47, v38, v39
	global_store_dwordx4 v1, v[44:47], s[42:43]
	v_pk_add_f32 v[16:17], v[16:17], v[152:153] neg_lo:[0,1] neg_hi:[0,1]
	v_pk_add_f32 v[18:19], v[18:19], v[154:155] neg_lo:[0,1] neg_hi:[0,1]
	v_pk_add_f32 v[20:21], v[20:21], v[156:157] neg_lo:[0,1] neg_hi:[0,1]
	v_pk_add_f32 v[22:23], v[22:23], v[158:159] neg_lo:[0,1] neg_hi:[0,1]
	s_add_u32 s42, s42, 0x1000
	s_addc_u32 s43, s43, 0
	s_add_u32 s78, s78, 0x2000
	s_addc_u32 s79, s79, 0
	s_add_i32 s82, s82, 1
	s_add_u32 s32, s32, 1
	s_sub_u32 s2, s2, 1
	s_cmp_eq_u32 s2, 0
	s_cbranch_scc1 .Lp5_pool_next_item
	s_add_u32 s67, s8, s32
	s_cmp_lt_u32 s67, s6
	s_cbranch_scc1 .Lp5_pool_div_4
	v_mov_b32_e32 v3, s10
	s_branch .Lp5_pool_inv_4

.Lp5_pool_inv_4:
	v_lshlrev_b32_e32 v24, 16, v80
	v_and_b32_e32 v25, 0xffff0000, v80
	v_lshlrev_b32_e32 v26, 16, v81
	v_and_b32_e32 v27, 0xffff0000, v81
	v_lshlrev_b32_e32 v28, 16, v82
	v_and_b32_e32 v29, 0xffff0000, v82
	v_lshlrev_b32_e32 v30, 16, v83
	v_and_b32_e32 v31, 0xffff0000, v83
	s_cmp_lt_i32 s82, 0
	s_cbranch_scc1 .Lp5_pool_nost_4
	global_store_dwordx4 v2, v[24:27], s[78:79]
	global_store_dwordx4 v2, v[28:31], s[78:79] offset:16
.Lp5_pool_nost_4:
	v_pk_add_f32 v[16:17], v[16:17], v[24:25]
	v_pk_add_f32 v[18:19], v[18:19], v[26:27]
	v_pk_add_f32 v[20:21], v[20:21], v[28:29]
	v_pk_add_f32 v[22:23], v[22:23], v[30:31]
	v_fma_f32 v32, v16, v3, -v24
	v_fma_f32 v33, v17, v3, -v25
	v_fma_f32 v34, v18, v3, -v26
	v_fma_f32 v35, v19, v3, -v27
	v_fma_f32 v36, v20, v3, -v28
	v_fma_f32 v37, v21, v3, -v29
	v_fma_f32 v38, v22, v3, -v30
	v_fma_f32 v39, v23, v3, -v31
	v_cvt_pk_bf16_f32 v40, v32, v33
	v_cvt_pk_bf16_f32 v41, v34, v35
	v_cvt_pk_bf16_f32 v42, v36, v37
	v_cvt_pk_bf16_f32 v43, v38, v39
	global_store_dwordx4 v1, v[40:43], s[42:43]
	v_pk_add_f32 v[16:17], v[16:17], v[160:161] neg_lo:[0,1] neg_hi:[0,1]
	v_pk_add_f32 v[18:19], v[18:19], v[162:163] neg_lo:[0,1] neg_hi:[0,1]
	v_pk_add_f32 v[20:21], v[20:21], v[164:165] neg_lo:[0,1] neg_hi:[0,1]
	v_pk_add_f32 v[22:23], v[22:23], v[166:167] neg_lo:[0,1] neg_hi:[0,1]
	s_add_u32 s42, s42, 0x1000
	s_addc_u32 s43, s43, 0
	s_add_u32 s78, s78, 0x2000
	s_addc_u32 s79, s79, 0
	s_add_i32 s82, s82, 1
	s_add_u32 s32, s32, 1
	s_sub_u32 s2, s2, 1
	s_cmp_eq_u32 s2, 0
	s_cbranch_scc1 .Lp5_pool_next_item
	s_add_u32 s67, s8, s32
	s_cmp_lt_u32 s67, s6
	s_cbranch_scc1 .Lp5_pool_div_5
	v_mov_b32_e32 v3, s10
	s_branch .Lp5_pool_inv_5

.Lp5_pool_inv_5:
	v_lshlrev_b32_e32 v24, 16, v84
	v_and_b32_e32 v25, 0xffff0000, v84
	v_lshlrev_b32_e32 v26, 16, v85
	v_and_b32_e32 v27, 0xffff0000, v85
	v_lshlrev_b32_e32 v28, 16, v86
	v_and_b32_e32 v29, 0xffff0000, v86
	v_lshlrev_b32_e32 v30, 16, v87
	v_and_b32_e32 v31, 0xffff0000, v87
	s_cmp_lt_i32 s82, 0
	s_cbranch_scc1 .Lp5_pool_nost_5
	global_store_dwordx4 v2, v[24:27], s[78:79]
	global_store_dwordx4 v2, v[28:31], s[78:79] offset:16
.Lp5_pool_nost_5:
	v_pk_add_f32 v[16:17], v[16:17], v[24:25]
	v_pk_add_f32 v[18:19], v[18:19], v[26:27]
	v_pk_add_f32 v[20:21], v[20:21], v[28:29]
	v_pk_add_f32 v[22:23], v[22:23], v[30:31]
	v_fma_f32 v32, v16, v3, -v24
	v_fma_f32 v33, v17, v3, -v25
	v_fma_f32 v34, v18, v3, -v26
	v_fma_f32 v35, v19, v3, -v27
	v_fma_f32 v36, v20, v3, -v28
	v_fma_f32 v37, v21, v3, -v29
	v_fma_f32 v38, v22, v3, -v30
	v_fma_f32 v39, v23, v3, -v31
	v_cvt_pk_bf16_f32 v44, v32, v33
	v_cvt_pk_bf16_f32 v45, v34, v35
	v_cvt_pk_bf16_f32 v46, v36, v37
	v_cvt_pk_bf16_f32 v47, v38, v39
	global_store_dwordx4 v1, v[44:47], s[42:43]
	v_pk_add_f32 v[16:17], v[16:17], v[168:169] neg_lo:[0,1] neg_hi:[0,1]
	v_pk_add_f32 v[18:19], v[18:19], v[170:171] neg_lo:[0,1] neg_hi:[0,1]
	v_pk_add_f32 v[20:21], v[20:21], v[172:173] neg_lo:[0,1] neg_hi:[0,1]
	v_pk_add_f32 v[22:23], v[22:23], v[174:175] neg_lo:[0,1] neg_hi:[0,1]
	s_add_u32 s42, s42, 0x1000
	s_addc_u32 s43, s43, 0
	s_add_u32 s78, s78, 0x2000
	s_addc_u32 s79, s79, 0
	s_add_i32 s82, s82, 1
	s_add_u32 s32, s32, 1
	s_sub_u32 s2, s2, 1
	s_cmp_eq_u32 s2, 0
	s_cbranch_scc1 .Lp5_pool_next_item
	s_add_u32 s67, s8, s32
	s_cmp_lt_u32 s67, s6
	s_cbranch_scc1 .Lp5_pool_div_6
	v_mov_b32_e32 v3, s10
	s_branch .Lp5_pool_inv_6

.Lp5_pool_inv_6:
	v_lshlrev_b32_e32 v24, 16, v88
	v_and_b32_e32 v25, 0xffff0000, v88
	v_lshlrev_b32_e32 v26, 16, v89
	v_and_b32_e32 v27, 0xffff0000, v89
	v_lshlrev_b32_e32 v28, 16, v90
	v_and_b32_e32 v29, 0xffff0000, v90
	v_lshlrev_b32_e32 v30, 16, v91
	v_and_b32_e32 v31, 0xffff0000, v91
	s_cmp_lt_i32 s82, 0
	s_cbranch_scc1 .Lp5_pool_nost_6
	global_store_dwordx4 v2, v[24:27], s[78:79]
	global_store_dwordx4 v2, v[28:31], s[78:79] offset:16
.Lp5_pool_nost_6:
	v_pk_add_f32 v[16:17], v[16:17], v[24:25]
	v_pk_add_f32 v[18:19], v[18:19], v[26:27]
	v_pk_add_f32 v[20:21], v[20:21], v[28:29]
	v_pk_add_f32 v[22:23], v[22:23], v[30:31]
	v_fma_f32 v32, v16, v3, -v24
	v_fma_f32 v33, v17, v3, -v25
	v_fma_f32 v34, v18, v3, -v26
	v_fma_f32 v35, v19, v3, -v27
	v_fma_f32 v36, v20, v3, -v28
	v_fma_f32 v37, v21, v3, -v29
	v_fma_f32 v38, v22, v3, -v30
	v_fma_f32 v39, v23, v3, -v31
	v_cvt_pk_bf16_f32 v40, v32, v33
	v_cvt_pk_bf16_f32 v41, v34, v35
	v_cvt_pk_bf16_f32 v42, v36, v37
	v_cvt_pk_bf16_f32 v43, v38, v39
	global_store_dwordx4 v1, v[40:43], s[42:43]
	v_pk_add_f32 v[16:17], v[16:17], v[176:177] neg_lo:[0,1] neg_hi:[0,1]
	v_pk_add_f32 v[18:19], v[18:19], v[178:179] neg_lo:[0,1] neg_hi:[0,1]
	v_pk_add_f32 v[20:21], v[20:21], v[180:181] neg_lo:[0,1] neg_hi:[0,1]
	v_pk_add_f32 v[22:23], v[22:23], v[182:183] neg_lo:[0,1] neg_hi:[0,1]
	s_add_u32 s42, s42, 0x1000
	s_addc_u32 s43, s43, 0
	s_add_u32 s78, s78, 0x2000
	s_addc_u32 s79, s79, 0
	s_add_i32 s82, s82, 1
	s_add_u32 s32, s32, 1
	s_sub_u32 s2, s2, 1
	s_cmp_eq_u32 s2, 0
	s_cbranch_scc1 .Lp5_pool_next_item
	s_add_u32 s67, s8, s32
	s_cmp_lt_u32 s67, s6
	s_cbranch_scc1 .Lp5_pool_div_7
	v_mov_b32_e32 v3, s10
	s_branch .Lp5_pool_inv_7

.Lp5_pool_inv_7:
	v_lshlrev_b32_e32 v24, 16, v92
	v_and_b32_e32 v25, 0xffff0000, v92
	v_lshlrev_b32_e32 v26, 16, v93
	v_and_b32_e32 v27, 0xffff0000, v93
	v_lshlrev_b32_e32 v28, 16, v94
	v_and_b32_e32 v29, 0xffff0000, v94
	v_lshlrev_b32_e32 v30, 16, v95
	v_and_b32_e32 v31, 0xffff0000, v95
	s_cmp_lt_i32 s82, 0
	s_cbranch_scc1 .Lp5_pool_nost_7
	global_store_dwordx4 v2, v[24:27], s[78:79]
	global_store_dwordx4 v2, v[28:31], s[78:79] offset:16
.Lp5_pool_nost_7:
	v_pk_add_f32 v[16:17], v[16:17], v[24:25]
	v_pk_add_f32 v[18:19], v[18:19], v[26:27]
	v_pk_add_f32 v[20:21], v[20:21], v[28:29]
	v_pk_add_f32 v[22:23], v[22:23], v[30:31]
	v_fma_f32 v32, v16, v3, -v24
	v_fma_f32 v33, v17, v3, -v25
	v_fma_f32 v34, v18, v3, -v26
	v_fma_f32 v35, v19, v3, -v27
	v_fma_f32 v36, v20, v3, -v28
	v_fma_f32 v37, v21, v3, -v29
	v_fma_f32 v38, v22, v3, -v30
	v_fma_f32 v39, v23, v3, -v31
	v_cvt_pk_bf16_f32 v44, v32, v33
	v_cvt_pk_bf16_f32 v45, v34, v35
	v_cvt_pk_bf16_f32 v46, v36, v37
	v_cvt_pk_bf16_f32 v47, v38, v39
	global_store_dwordx4 v1, v[44:47], s[42:43]
	v_pk_add_f32 v[16:17], v[16:17], v[184:185] neg_lo:[0,1] neg_hi:[0,1]
	v_pk_add_f32 v[18:19], v[18:19], v[186:187] neg_lo:[0,1] neg_hi:[0,1]
	v_pk_add_f32 v[20:21], v[20:21], v[188:189] neg_lo:[0,1] neg_hi:[0,1]
	v_pk_add_f32 v[22:23], v[22:23], v[190:191] neg_lo:[0,1] neg_hi:[0,1]
	s_add_u32 s42, s42, 0x1000
	s_addc_u32 s43, s43, 0
	s_add_u32 s78, s78, 0x2000
	s_addc_u32 s79, s79, 0
	s_add_i32 s82, s82, 1
	s_add_u32 s32, s32, 1
	s_sub_u32 s2, s2, 1
	s_cmp_eq_u32 s2, 0
	s_cbranch_scc1 .Lp5_pool_next_item
	s_add_u32 s67, s8, s32
	s_cmp_lt_u32 s67, s6
	s_cbranch_scc1 .Lp5_pool_div_8
	v_mov_b32_e32 v3, s10
	s_branch .Lp5_pool_inv_8

.Lp5_pool_inv_8:
	v_lshlrev_b32_e32 v24, 16, v96
	v_and_b32_e32 v25, 0xffff0000, v96
	v_lshlrev_b32_e32 v26, 16, v97
	v_and_b32_e32 v27, 0xffff0000, v97
	v_lshlrev_b32_e32 v28, 16, v98
	v_and_b32_e32 v29, 0xffff0000, v98
	v_lshlrev_b32_e32 v30, 16, v99
	v_and_b32_e32 v31, 0xffff0000, v99
	s_cmp_lt_i32 s82, 0
	s_cbranch_scc1 .Lp5_pool_nost_8
	global_store_dwordx4 v2, v[24:27], s[78:79]
	global_store_dwordx4 v2, v[28:31], s[78:79] offset:16
.Lp5_pool_nost_8:
	v_pk_add_f32 v[16:17], v[16:17], v[24:25]
	v_pk_add_f32 v[18:19], v[18:19], v[26:27]
	v_pk_add_f32 v[20:21], v[20:21], v[28:29]
	v_pk_add_f32 v[22:23], v[22:23], v[30:31]
	v_fma_f32 v32, v16, v3, -v24
	v_fma_f32 v33, v17, v3, -v25
	v_fma_f32 v34, v18, v3, -v26
	v_fma_f32 v35, v19, v3, -v27
	v_fma_f32 v36, v20, v3, -v28
	v_fma_f32 v37, v21, v3, -v29
	v_fma_f32 v38, v22, v3, -v30
	v_fma_f32 v39, v23, v3, -v31
	v_cvt_pk_bf16_f32 v40, v32, v33
	v_cvt_pk_bf16_f32 v41, v34, v35
	v_cvt_pk_bf16_f32 v42, v36, v37
	v_cvt_pk_bf16_f32 v43, v38, v39
	global_store_dwordx4 v1, v[40:43], s[42:43]
	v_pk_add_f32 v[16:17], v[16:17], v[192:193] neg_lo:[0,1] neg_hi:[0,1]
	v_pk_add_f32 v[18:19], v[18:19], v[194:195] neg_lo:[0,1] neg_hi:[0,1]
	v_pk_add_f32 v[20:21], v[20:21], v[196:197] neg_lo:[0,1] neg_hi:[0,1]
	v_pk_add_f32 v[22:23], v[22:23], v[198:199] neg_lo:[0,1] neg_hi:[0,1]
	s_add_u32 s42, s42, 0x1000
	s_addc_u32 s43, s43, 0
	s_add_u32 s78, s78, 0x2000
	s_addc_u32 s79, s79, 0
	s_add_i32 s82, s82, 1
	s_add_u32 s32, s32, 1
	s_sub_u32 s2, s2, 1
	s_cmp_eq_u32 s2, 0
	s_cbranch_scc1 .Lp5_pool_next_item
	s_add_u32 s67, s8, s32
	s_cmp_lt_u32 s67, s6
	s_cbranch_scc1 .Lp5_pool_div_9
	v_mov_b32_e32 v3, s10
	s_branch .Lp5_pool_inv_9

.Lp5_pool_inv_9:
	v_lshlrev_b32_e32 v24, 16, v100
	v_and_b32_e32 v25, 0xffff0000, v100
	v_lshlrev_b32_e32 v26, 16, v101
	v_and_b32_e32 v27, 0xffff0000, v101
	v_lshlrev_b32_e32 v28, 16, v102
	v_and_b32_e32 v29, 0xffff0000, v102
	v_lshlrev_b32_e32 v30, 16, v103
	v_and_b32_e32 v31, 0xffff0000, v103
	s_cmp_lt_i32 s82, 0
	s_cbranch_scc1 .Lp5_pool_nost_9
	global_store_dwordx4 v2, v[24:27], s[78:79]
	global_store_dwordx4 v2, v[28:31], s[78:79] offset:16
.Lp5_pool_nost_9:
	v_pk_add_f32 v[16:17], v[16:17], v[24:25]
	v_pk_add_f32 v[18:19], v[18:19], v[26:27]
	v_pk_add_f32 v[20:21], v[20:21], v[28:29]
	v_pk_add_f32 v[22:23], v[22:23], v[30:31]
	v_fma_f32 v32, v16, v3, -v24
	v_fma_f32 v33, v17, v3, -v25
	v_fma_f32 v34, v18, v3, -v26
	v_fma_f32 v35, v19, v3, -v27
	v_fma_f32 v36, v20, v3, -v28
	v_fma_f32 v37, v21, v3, -v29
	v_fma_f32 v38, v22, v3, -v30
	v_fma_f32 v39, v23, v3, -v31
	v_cvt_pk_bf16_f32 v44, v32, v33
	v_cvt_pk_bf16_f32 v45, v34, v35
	v_cvt_pk_bf16_f32 v46, v36, v37
	v_cvt_pk_bf16_f32 v47, v38, v39
	global_store_dwordx4 v1, v[44:47], s[42:43]
	v_pk_add_f32 v[16:17], v[16:17], v[200:201] neg_lo:[0,1] neg_hi:[0,1]
	v_pk_add_f32 v[18:19], v[18:19], v[202:203] neg_lo:[0,1] neg_hi:[0,1]
	v_pk_add_f32 v[20:21], v[20:21], v[204:205] neg_lo:[0,1] neg_hi:[0,1]
	v_pk_add_f32 v[22:23], v[22:23], v[206:207] neg_lo:[0,1] neg_hi:[0,1]
	s_add_u32 s42, s42, 0x1000
	s_addc_u32 s43, s43, 0
	s_add_u32 s78, s78, 0x2000
	s_addc_u32 s79, s79, 0
	s_add_i32 s82, s82, 1
	s_add_u32 s32, s32, 1
	s_sub_u32 s2, s2, 1
	s_cmp_eq_u32 s2, 0
	s_cbranch_scc1 .Lp5_pool_next_item
	s_add_u32 s67, s8, s32
	s_cmp_lt_u32 s67, s6
	s_cbranch_scc1 .Lp5_pool_div_10
	v_mov_b32_e32 v3, s10
	s_branch .Lp5_pool_inv_10

.Lp5_pool_inv_10:
	v_lshlrev_b32_e32 v24, 16, v104
	v_and_b32_e32 v25, 0xffff0000, v104
	v_lshlrev_b32_e32 v26, 16, v105
	v_and_b32_e32 v27, 0xffff0000, v105
	v_lshlrev_b32_e32 v28, 16, v106
	v_and_b32_e32 v29, 0xffff0000, v106
	v_lshlrev_b32_e32 v30, 16, v107
	v_and_b32_e32 v31, 0xffff0000, v107
	s_cmp_lt_i32 s82, 0
	s_cbranch_scc1 .Lp5_pool_nost_10
	global_store_dwordx4 v2, v[24:27], s[78:79]
	global_store_dwordx4 v2, v[28:31], s[78:79] offset:16
.Lp5_pool_nost_10:
	v_pk_add_f32 v[16:17], v[16:17], v[24:25]
	v_pk_add_f32 v[18:19], v[18:19], v[26:27]
	v_pk_add_f32 v[20:21], v[20:21], v[28:29]
	v_pk_add_f32 v[22:23], v[22:23], v[30:31]
	v_fma_f32 v32, v16, v3, -v24
	v_fma_f32 v33, v17, v3, -v25
	v_fma_f32 v34, v18, v3, -v26
	v_fma_f32 v35, v19, v3, -v27
	v_fma_f32 v36, v20, v3, -v28
	v_fma_f32 v37, v21, v3, -v29
	v_fma_f32 v38, v22, v3, -v30
	v_fma_f32 v39, v23, v3, -v31
	v_cvt_pk_bf16_f32 v40, v32, v33
	v_cvt_pk_bf16_f32 v41, v34, v35
	v_cvt_pk_bf16_f32 v42, v36, v37
	v_cvt_pk_bf16_f32 v43, v38, v39
	global_store_dwordx4 v1, v[40:43], s[42:43]
	v_pk_add_f32 v[16:17], v[16:17], v[208:209] neg_lo:[0,1] neg_hi:[0,1]
	v_pk_add_f32 v[18:19], v[18:19], v[210:211] neg_lo:[0,1] neg_hi:[0,1]
	v_pk_add_f32 v[20:21], v[20:21], v[212:213] neg_lo:[0,1] neg_hi:[0,1]
	v_pk_add_f32 v[22:23], v[22:23], v[214:215] neg_lo:[0,1] neg_hi:[0,1]
	s_add_u32 s42, s42, 0x1000
	s_addc_u32 s43, s43, 0
	s_add_u32 s78, s78, 0x2000
	s_addc_u32 s79, s79, 0
	s_add_i32 s82, s82, 1
	s_add_u32 s32, s32, 1
	s_sub_u32 s2, s2, 1
	s_cmp_eq_u32 s2, 0
	s_cbranch_scc1 .Lp5_pool_next_item
	s_add_u32 s67, s8, s32
	s_cmp_lt_u32 s67, s6
	s_cbranch_scc1 .Lp5_pool_div_11
	v_mov_b32_e32 v3, s10
	s_branch .Lp5_pool_inv_11

.Lp5_pool_inv_11:
	v_lshlrev_b32_e32 v24, 16, v108
	v_and_b32_e32 v25, 0xffff0000, v108
	v_lshlrev_b32_e32 v26, 16, v109
	v_and_b32_e32 v27, 0xffff0000, v109
	v_lshlrev_b32_e32 v28, 16, v110
	v_and_b32_e32 v29, 0xffff0000, v110
	v_lshlrev_b32_e32 v30, 16, v111
	v_and_b32_e32 v31, 0xffff0000, v111
	s_cmp_lt_i32 s82, 0
	s_cbranch_scc1 .Lp5_pool_nost_11
	global_store_dwordx4 v2, v[24:27], s[78:79]
	global_store_dwordx4 v2, v[28:31], s[78:79] offset:16
.Lp5_pool_nost_11:
	v_pk_add_f32 v[16:17], v[16:17], v[24:25]
	v_pk_add_f32 v[18:19], v[18:19], v[26:27]
	v_pk_add_f32 v[20:21], v[20:21], v[28:29]
	v_pk_add_f32 v[22:23], v[22:23], v[30:31]
	v_fma_f32 v32, v16, v3, -v24
	v_fma_f32 v33, v17, v3, -v25
	v_fma_f32 v34, v18, v3, -v26
	v_fma_f32 v35, v19, v3, -v27
	v_fma_f32 v36, v20, v3, -v28
	v_fma_f32 v37, v21, v3, -v29
	v_fma_f32 v38, v22, v3, -v30
	v_fma_f32 v39, v23, v3, -v31
	v_cvt_pk_bf16_f32 v44, v32, v33
	v_cvt_pk_bf16_f32 v45, v34, v35
	v_cvt_pk_bf16_f32 v46, v36, v37
	v_cvt_pk_bf16_f32 v47, v38, v39
	global_store_dwordx4 v1, v[44:47], s[42:43]
	v_pk_add_f32 v[16:17], v[16:17], v[216:217] neg_lo:[0,1] neg_hi:[0,1]
	v_pk_add_f32 v[18:19], v[18:19], v[218:219] neg_lo:[0,1] neg_hi:[0,1]
	v_pk_add_f32 v[20:21], v[20:21], v[220:221] neg_lo:[0,1] neg_hi:[0,1]
	v_pk_add_f32 v[22:23], v[22:23], v[222:223] neg_lo:[0,1] neg_hi:[0,1]
	s_add_u32 s42, s42, 0x1000
	s_addc_u32 s43, s43, 0
	s_add_u32 s78, s78, 0x2000
	s_addc_u32 s79, s79, 0
	s_add_i32 s82, s82, 1
	s_add_u32 s32, s32, 1
	s_sub_u32 s2, s2, 1
	s_cmp_eq_u32 s2, 0
	s_cbranch_scc1 .Lp5_pool_next_item
	s_add_u32 s67, s8, s32
	s_cmp_lt_u32 s67, s6
	s_cbranch_scc1 .Lp5_pool_div_12
	v_mov_b32_e32 v3, s10
	s_branch .Lp5_pool_inv_12

.Lp5_pool_inv_12:
	v_lshlrev_b32_e32 v24, 16, v112
	v_and_b32_e32 v25, 0xffff0000, v112
	v_lshlrev_b32_e32 v26, 16, v113
	v_and_b32_e32 v27, 0xffff0000, v113
	v_lshlrev_b32_e32 v28, 16, v114
	v_and_b32_e32 v29, 0xffff0000, v114
	v_lshlrev_b32_e32 v30, 16, v115
	v_and_b32_e32 v31, 0xffff0000, v115
	s_cmp_lt_i32 s82, 0
	s_cbranch_scc1 .Lp5_pool_nost_12
	global_store_dwordx4 v2, v[24:27], s[78:79]
	global_store_dwordx4 v2, v[28:31], s[78:79] offset:16
.Lp5_pool_nost_12:
	v_pk_add_f32 v[16:17], v[16:17], v[24:25]
	v_pk_add_f32 v[18:19], v[18:19], v[26:27]
	v_pk_add_f32 v[20:21], v[20:21], v[28:29]
	v_pk_add_f32 v[22:23], v[22:23], v[30:31]
	v_fma_f32 v32, v16, v3, -v24
	v_fma_f32 v33, v17, v3, -v25
	v_fma_f32 v34, v18, v3, -v26
	v_fma_f32 v35, v19, v3, -v27
	v_fma_f32 v36, v20, v3, -v28
	v_fma_f32 v37, v21, v3, -v29
	v_fma_f32 v38, v22, v3, -v30
	v_fma_f32 v39, v23, v3, -v31
	v_cvt_pk_bf16_f32 v40, v32, v33
	v_cvt_pk_bf16_f32 v41, v34, v35
	v_cvt_pk_bf16_f32 v42, v36, v37
	v_cvt_pk_bf16_f32 v43, v38, v39
	global_store_dwordx4 v1, v[40:43], s[42:43]
	v_pk_add_f32 v[16:17], v[16:17], v[224:225] neg_lo:[0,1] neg_hi:[0,1]
	v_pk_add_f32 v[18:19], v[18:19], v[226:227] neg_lo:[0,1] neg_hi:[0,1]
	v_pk_add_f32 v[20:21], v[20:21], v[228:229] neg_lo:[0,1] neg_hi:[0,1]
	v_pk_add_f32 v[22:23], v[22:23], v[230:231] neg_lo:[0,1] neg_hi:[0,1]
	s_add_u32 s42, s42, 0x1000
	s_addc_u32 s43, s43, 0
	s_add_u32 s78, s78, 0x2000
	s_addc_u32 s79, s79, 0
	s_add_i32 s82, s82, 1
	s_add_u32 s32, s32, 1
	s_sub_u32 s2, s2, 1
	s_cmp_eq_u32 s2, 0
	s_cbranch_scc1 .Lp5_pool_next_item
	s_add_u32 s67, s8, s32
	s_cmp_lt_u32 s67, s6
	s_cbranch_scc1 .Lp5_pool_div_13
	v_mov_b32_e32 v3, s10
	s_branch .Lp5_pool_inv_13

.Lp5_pool_inv_13:
	v_lshlrev_b32_e32 v24, 16, v116
	v_and_b32_e32 v25, 0xffff0000, v116
	v_lshlrev_b32_e32 v26, 16, v117
	v_and_b32_e32 v27, 0xffff0000, v117
	v_lshlrev_b32_e32 v28, 16, v118
	v_and_b32_e32 v29, 0xffff0000, v118
	v_lshlrev_b32_e32 v30, 16, v119
	v_and_b32_e32 v31, 0xffff0000, v119
	s_cmp_lt_i32 s82, 0
	s_cbranch_scc1 .Lp5_pool_nost_13
	global_store_dwordx4 v2, v[24:27], s[78:79]
	global_store_dwordx4 v2, v[28:31], s[78:79] offset:16
.Lp5_pool_nost_13:
	v_pk_add_f32 v[16:17], v[16:17], v[24:25]
	v_pk_add_f32 v[18:19], v[18:19], v[26:27]
	v_pk_add_f32 v[20:21], v[20:21], v[28:29]
	v_pk_add_f32 v[22:23], v[22:23], v[30:31]
	v_fma_f32 v32, v16, v3, -v24
	v_fma_f32 v33, v17, v3, -v25
	v_fma_f32 v34, v18, v3, -v26
	v_fma_f32 v35, v19, v3, -v27
	v_fma_f32 v36, v20, v3, -v28
	v_fma_f32 v37, v21, v3, -v29
	v_fma_f32 v38, v22, v3, -v30
	v_fma_f32 v39, v23, v3, -v31
	v_cvt_pk_bf16_f32 v44, v32, v33
	v_cvt_pk_bf16_f32 v45, v34, v35
	v_cvt_pk_bf16_f32 v46, v36, v37
	v_cvt_pk_bf16_f32 v47, v38, v39
	global_store_dwordx4 v1, v[44:47], s[42:43]
	v_pk_add_f32 v[16:17], v[16:17], v[232:233] neg_lo:[0,1] neg_hi:[0,1]
	v_pk_add_f32 v[18:19], v[18:19], v[234:235] neg_lo:[0,1] neg_hi:[0,1]
	v_pk_add_f32 v[20:21], v[20:21], v[236:237] neg_lo:[0,1] neg_hi:[0,1]
	v_pk_add_f32 v[22:23], v[22:23], v[238:239] neg_lo:[0,1] neg_hi:[0,1]
	s_add_u32 s42, s42, 0x1000
	s_addc_u32 s43, s43, 0
	s_add_u32 s78, s78, 0x2000
	s_addc_u32 s79, s79, 0
	s_add_i32 s82, s82, 1
	s_add_u32 s32, s32, 1
	s_sub_u32 s2, s2, 1
	s_cmp_eq_u32 s2, 0
	s_cbranch_scc1 .Lp5_pool_next_item
	s_add_u32 s67, s8, s32
	s_cmp_lt_u32 s67, s6
	s_cbranch_scc1 .Lp5_pool_div_14
	v_mov_b32_e32 v3, s10
	s_branch .Lp5_pool_inv_14

.Lp5_pool_inv_14:
	v_lshlrev_b32_e32 v24, 16, v120
	v_and_b32_e32 v25, 0xffff0000, v120
	v_lshlrev_b32_e32 v26, 16, v121
	v_and_b32_e32 v27, 0xffff0000, v121
	v_lshlrev_b32_e32 v28, 16, v122
	v_and_b32_e32 v29, 0xffff0000, v122
	v_lshlrev_b32_e32 v30, 16, v123
	v_and_b32_e32 v31, 0xffff0000, v123
	s_cmp_lt_i32 s82, 0
	s_cbranch_scc1 .Lp5_pool_nost_14
	global_store_dwordx4 v2, v[24:27], s[78:79]
	global_store_dwordx4 v2, v[28:31], s[78:79] offset:16
.Lp5_pool_nost_14:
	v_pk_add_f32 v[16:17], v[16:17], v[24:25]
	v_pk_add_f32 v[18:19], v[18:19], v[26:27]
	v_pk_add_f32 v[20:21], v[20:21], v[28:29]
	v_pk_add_f32 v[22:23], v[22:23], v[30:31]
	v_fma_f32 v32, v16, v3, -v24
	v_fma_f32 v33, v17, v3, -v25
	v_fma_f32 v34, v18, v3, -v26
	v_fma_f32 v35, v19, v3, -v27
	v_fma_f32 v36, v20, v3, -v28
	v_fma_f32 v37, v21, v3, -v29
	v_fma_f32 v38, v22, v3, -v30
	v_fma_f32 v39, v23, v3, -v31
	v_cvt_pk_bf16_f32 v40, v32, v33
	v_cvt_pk_bf16_f32 v41, v34, v35
	v_cvt_pk_bf16_f32 v42, v36, v37
	v_cvt_pk_bf16_f32 v43, v38, v39
	global_store_dwordx4 v1, v[40:43], s[42:43]
	v_pk_add_f32 v[16:17], v[16:17], v[240:241] neg_lo:[0,1] neg_hi:[0,1]
	v_pk_add_f32 v[18:19], v[18:19], v[242:243] neg_lo:[0,1] neg_hi:[0,1]
	v_pk_add_f32 v[20:21], v[20:21], v[244:245] neg_lo:[0,1] neg_hi:[0,1]
	v_pk_add_f32 v[22:23], v[22:23], v[246:247] neg_lo:[0,1] neg_hi:[0,1]
	s_add_u32 s42, s42, 0x1000
	s_addc_u32 s43, s43, 0
	s_add_u32 s78, s78, 0x2000
	s_addc_u32 s79, s79, 0
	s_add_i32 s82, s82, 1
	s_add_u32 s32, s32, 1
	s_sub_u32 s2, s2, 1
	s_cmp_eq_u32 s2, 0
	s_cbranch_scc1 .Lp5_pool_next_item
	s_add_u32 s67, s8, s32
	s_cmp_lt_u32 s67, s6
	s_cbranch_scc1 .Lp5_pool_div_15
	v_mov_b32_e32 v3, s10
	s_branch .Lp5_pool_inv_15

.Lp5_pool_inv_15:
	v_lshlrev_b32_e32 v24, 16, v124
	v_and_b32_e32 v25, 0xffff0000, v124
	v_lshlrev_b32_e32 v26, 16, v125
	v_and_b32_e32 v27, 0xffff0000, v125
	v_lshlrev_b32_e32 v28, 16, v126
	v_and_b32_e32 v29, 0xffff0000, v126
	v_lshlrev_b32_e32 v30, 16, v127
	v_and_b32_e32 v31, 0xffff0000, v127
	s_cmp_lt_i32 s82, 0
	s_cbranch_scc1 .Lp5_pool_nost_15
	global_store_dwordx4 v2, v[24:27], s[78:79]
	global_store_dwordx4 v2, v[28:31], s[78:79] offset:16
.Lp5_pool_nost_15:
	v_pk_add_f32 v[16:17], v[16:17], v[24:25]
	v_pk_add_f32 v[18:19], v[18:19], v[26:27]
	v_pk_add_f32 v[20:21], v[20:21], v[28:29]
	v_pk_add_f32 v[22:23], v[22:23], v[30:31]
	v_fma_f32 v32, v16, v3, -v24
	v_fma_f32 v33, v17, v3, -v25
	v_fma_f32 v34, v18, v3, -v26
	v_fma_f32 v35, v19, v3, -v27
	v_fma_f32 v36, v20, v3, -v28
	v_fma_f32 v37, v21, v3, -v29
	v_fma_f32 v38, v22, v3, -v30
	v_fma_f32 v39, v23, v3, -v31
	v_cvt_pk_bf16_f32 v44, v32, v33
	v_cvt_pk_bf16_f32 v45, v34, v35
	v_cvt_pk_bf16_f32 v46, v36, v37
	v_cvt_pk_bf16_f32 v47, v38, v39
	global_store_dwordx4 v1, v[44:47], s[42:43]
	v_pk_add_f32 v[16:17], v[16:17], v[48:49] neg_lo:[0,1] neg_hi:[0,1]
	v_pk_add_f32 v[18:19], v[18:19], v[50:51] neg_lo:[0,1] neg_hi:[0,1]
	v_pk_add_f32 v[20:21], v[20:21], v[52:53] neg_lo:[0,1] neg_hi:[0,1]
	v_pk_add_f32 v[22:23], v[22:23], v[54:55] neg_lo:[0,1] neg_hi:[0,1]
	s_add_u32 s42, s42, 0x1000
	s_addc_u32 s43, s43, 0
	s_add_u32 s78, s78, 0x2000
	s_addc_u32 s79, s79, 0
	s_add_i32 s82, s82, 1
	s_add_u32 s32, s32, 1
	s_sub_u32 s2, s2, 1
	s_add_u32 s61, s61, 1
	s_cmp_lg_u32 s2, 0
	s_cbranch_scc1 .Lp5_pool_block

.Lp5_conv_outer:
	s_cmp_ge_u32 s0, 0x1a000
	s_cbranch_scc1 .Lp5_conv_exit
	s_cmp_ge_u32 s0, 0x18000
	s_cbranch_scc1 .Lp5_conv_sample
	s_lshr_b32 s58, s0, 9
	s_and_b32 s60, s0, 0x1ff
	s_cmp_ge_u32 s58, 48
	s_cselect_b32 s59, 1, 0
	s_cmp_ge_u32 s58, 96
	s_cselect_b32 s46, 1, 0
	s_add_u32 s59, s59, s46
	s_cmp_ge_u32 s58, 144
	s_cselect_b32 s46, 1, 0
	s_add_u32 s59, s59, s46
	s_mul_i32 s46, s59, 48
	s_sub_u32 s58, s58, s46
	s_mul_i32 s1, s58, 43
	s_movk_i32 s2, 43
	s_mul_i32 s3, s59, 0x810
	s_mov_b32 s9, 0
	s_mov_b64 s[52:53], 0
	s_mul_i32 s46, s59, 0xc000
	s_add_u32 s46, s46, 0x8478000
	s_sub_i32 s82, s1, 2061
	s_branch .Lp5_conv_item
.Lp5_conv_sample:
	s_sub_u32 s46, s0, 0x18000
	s_and_b32 s60, s46, 0x1ff
	s_lshr_b32 s58, s46, 9
	s_lshr_b32 s59, s58, 1
	s_and_b32 s1, s58, 1
	s_lshl_b32 s1, s1, 4
	s_movk_i32 s2, 16
	s_lshl_b32 s3, s59, 5
	s_add_u32 s3, s3, 0x2040
	s_mov_b32 s9, 1
	v_readlane_b32 s52, v255, 13
	v_readlane_b32 s53, v255, 14
	s_mul_i32 s46, s59, 0xc000
	s_nop 1
	s_add_u32 s52, s52, s46
	s_addc_u32 s53, s53, 0
	s_add_u32 s46, s46, 0x85a8000
	s_sub_i32 s82, s1, 29
.Lp5_conv_item:
	s_lshl_b32 s47, s82, 14
	s_add_i32 s46, s46, s47
	s_ashr_i32 s47, s46, 31
	s_add_u32 s78, s86, s46
	s_addc_u32 s79, s87, s47
	v_add_u32_e32 v1, s60, v0
	v_lshlrev_b32_e32 v2, 5, v1
	v_lshlrev_b32_e32 v1, 4, v1
	s_mov_b64 s[20:21], s[62:63]
	global_load_dwordx4 v[128:131], v2, s[20:21]
	global_load_dwordx4 v[132:135], v2, s[20:21] offset:16
	s_add_u32 s20, s20, 0x4000
	s_addc_u32 s21, s21, 0
	global_load_dwordx4 v[136:139], v2, s[20:21]
	global_load_dwordx4 v[140:143], v2, s[20:21] offset:16
	s_add_u32 s20, s20, 0x4000
	s_addc_u32 s21, s21, 0
	global_load_dwordx4 v[144:147], v2, s[20:21]
	global_load_dwordx4 v[148:151], v2, s[20:21] offset:16
	s_add_u32 s20, s20, 0x4000
	s_addc_u32 s21, s21, 0
	global_load_dwordx4 v[152:155], v2, s[20:21]
	global_load_dwordx4 v[156:159], v2, s[20:21] offset:16
	s_add_u32 s20, s20, 0x4000
	s_addc_u32 s21, s21, 0
	global_load_dwordx4 v[160:163], v2, s[64:65]
	global_load_dwordx4 v[164:167], v2, s[64:65] offset:16
	s_add_i32 s29, s1, -3
	s_cmp_lt_i32 s29, 0
	s_cbranch_scc1 .Lp5_conv_hneg_0
	s_add_u32 s46, s3, s29
	s_mul_i32 s46, s46, 0x5000
	s_add_u32 s22, s54, s46
	s_addc_u32 s23, s55, 0
	global_load_dwordx4 v[180:183], v1, s[22:23]
	s_branch .Lp5_conv_hnext_0

.Lp5_conv_hu_2:
.Lp5_conv_rows:
	s_cmp_eq_u32 s2, 0
	s_cbranch_scc1 .Lp5_conv_next_item
	v_lshlrev_b32_e32 v168, 16, v64
	v_and_b32_e32 v169, 0xffff0000, v64
	v_lshlrev_b32_e32 v170, 16, v65
	v_and_b32_e32 v171, 0xffff0000, v65
	v_lshlrev_b32_e32 v172, 16, v66
	v_and_b32_e32 v173, 0xffff0000, v66
	v_lshlrev_b32_e32 v174, 16, v67
	v_and_b32_e32 v175, 0xffff0000, v67
	s_cmp_lt_i32 s82, 0
	s_cbranch_scc1 .Lp5_conv_nost_0
	global_store_dwordx4 v2, v[168:171], s[78:79]
	global_store_dwordx4 v2, v[172:175], s[78:79] offset:16
.Lp5_conv_nost_0:
	v_fma_f32 v200, v128, v176, v160
	v_fma_f32 v201, v129, v177, v161
	v_fma_f32 v202, v130, v178, v162
	v_fma_f32 v203, v131, v179, v163
	v_fma_f32 v204, v132, v180, v164
	v_fma_f32 v205, v133, v181, v165
	v_fma_f32 v206, v134, v182, v166
	v_fma_f32 v207, v135, v183, v167
	v_fmac_f32_e32 v200, v136, v184
	v_fmac_f32_e32 v201, v137, v185
	v_fmac_f32_e32 v202, v138, v186
	v_fmac_f32_e32 v203, v139, v187
	v_fmac_f32_e32 v204, v140, v188
	v_fmac_f32_e32 v205, v141, v189
	v_fmac_f32_e32 v206, v142, v190
	v_fmac_f32_e32 v207, v143, v191
	v_fmac_f32_e32 v200, v144, v192
	v_fmac_f32_e32 v201, v145, v193
	v_fmac_f32_e32 v202, v146, v194
	v_fmac_f32_e32 v203, v147, v195
	v_fmac_f32_e32 v204, v148, v196
	v_fmac_f32_e32 v205, v149, v197
	v_fmac_f32_e32 v206, v150, v198
	v_fmac_f32_e32 v207, v151, v199
	v_fmac_f32_e32 v200, v152, v168
	v_fmac_f32_e32 v201, v153, v169
	v_fmac_f32_e32 v202, v154, v170
	v_fmac_f32_e32 v203, v155, v171
	v_fmac_f32_e32 v204, v156, v172
	v_fmac_f32_e32 v205, v157, v173
	v_fmac_f32_e32 v206, v158, v174
	v_fmac_f32_e32 v207, v159, v175
	v_cvt_pk_bf16_f32 v40, v200, v201
	v_cvt_pk_bf16_f32 v41, v202, v203
	v_cvt_pk_bf16_f32 v42, v204, v205
	v_cvt_pk_bf16_f32 v43, v206, v207
	global_store_dwordx4 v1, v[40:43], s[42:43]
	s_add_u32 s42, s42, 0x2000
	s_addc_u32 s43, s43, 0
	s_add_u32 s78, s78, 0x4000
	s_addc_u32 s79, s79, 0
	s_add_i32 s82, s82, 1
	s_add_u32 s32, s32, 1
	s_sub_u32 s2, s2, 1
	s_cmp_eq_u32 s2, 0
	s_cbranch_scc1 .Lp5_conv_next_item
	v_lshlrev_b32_e32 v176, 16, v68
	v_and_b32_e32 v177, 0xffff0000, v68
	v_lshlrev_b32_e32 v178, 16, v69
	v_and_b32_e32 v179, 0xffff0000, v69
	v_lshlrev_b32_e32 v180, 16, v70
	v_and_b32_e32 v181, 0xffff0000, v70
	v_lshlrev_b32_e32 v182, 16, v71
	v_and_b32_e32 v183, 0xffff0000, v71
	s_cmp_lt_i32 s82, 0
	s_cbranch_scc1 .Lp5_conv_nost_1
	global_store_dwordx4 v2, v[176:179], s[78:79]
	global_store_dwordx4 v2, v[180:183], s[78:79] offset:16
.Lp5_conv_nost_1:
	v_fma_f32 v200, v128, v184, v160
	v_fma_f32 v201, v129, v185, v161
	v_fma_f32 v202, v130, v186, v162
	v_fma_f32 v203, v131, v187, v163
	v_fma_f32 v204, v132, v188, v164
	v_fma_f32 v205, v133, v189, v165
	v_fma_f32 v206, v134, v190, v166
	v_fma_f32 v207, v135, v191, v167
	v_fmac_f32_e32 v200, v136, v192
	v_fmac_f32_e32 v201, v137, v193
	v_fmac_f32_e32 v202, v138, v194
	v_fmac_f32_e32 v203, v139, v195
	v_fmac_f32_e32 v204, v140, v196
	v_fmac_f32_e32 v205, v141, v197
	v_fmac_f32_e32 v206, v142, v198
	v_fmac_f32_e32 v207, v143, v199
	v_fmac_f32_e32 v200, v144, v168
	v_fmac_f32_e32 v201, v145, v169
	v_fmac_f32_e32 v202, v146, v170
	v_fmac_f32_e32 v203, v147, v171
	v_fmac_f32_e32 v204, v148, v172
	v_fmac_f32_e32 v205, v149, v173
	v_fmac_f32_e32 v206, v150, v174
	v_fmac_f32_e32 v207, v151, v175
	v_fmac_f32_e32 v200, v152, v176
	v_fmac_f32_e32 v201, v153, v177
	v_fmac_f32_e32 v202, v154, v178
	v_fmac_f32_e32 v203, v155, v179
	v_fmac_f32_e32 v204, v156, v180
	v_fmac_f32_e32 v205, v157, v181
	v_fmac_f32_e32 v206, v158, v182
	v_fmac_f32_e32 v207, v159, v183
	v_cvt_pk_bf16_f32 v44, v200, v201
	v_cvt_pk_bf16_f32 v45, v202, v203
	v_cvt_pk_bf16_f32 v46, v204, v205
	v_cvt_pk_bf16_f32 v47, v206, v207
	global_store_dwordx4 v1, v[44:47], s[42:43]
	s_add_u32 s42, s42, 0x2000
	s_addc_u32 s43, s43, 0
	s_add_u32 s78, s78, 0x4000
	s_addc_u32 s79, s79, 0
	s_add_i32 s82, s82, 1
	s_add_u32 s32, s32, 1
	s_sub_u32 s2, s2, 1
	s_cmp_eq_u32 s2, 0
	s_cbranch_scc1 .Lp5_conv_next_item
	v_lshlrev_b32_e32 v184, 16, v72
	v_and_b32_e32 v185, 0xffff0000, v72
	v_lshlrev_b32_e32 v186, 16, v73
	v_and_b32_e32 v187, 0xffff0000, v73
	v_lshlrev_b32_e32 v188, 16, v74
	v_and_b32_e32 v189, 0xffff0000, v74
	v_lshlrev_b32_e32 v190, 16, v75
	v_and_b32_e32 v191, 0xffff0000, v75
	s_cmp_lt_i32 s82, 0
	s_cbranch_scc1 .Lp5_conv_nost_2
	global_store_dwordx4 v2, v[184:187], s[78:79]
	global_store_dwordx4 v2, v[188:191], s[78:79] offset:16
.Lp5_conv_nost_2:
	v_fma_f32 v200, v128, v192, v160
	v_fma_f32 v201, v129, v193, v161
	v_fma_f32 v202, v130, v194, v162
	v_fma_f32 v203, v131, v195, v163
	v_fma_f32 v204, v132, v196, v164
	v_fma_f32 v205, v133, v197, v165
	v_fma_f32 v206, v134, v198, v166
	v_fma_f32 v207, v135, v199, v167
	v_fmac_f32_e32 v200, v136, v168
	v_fmac_f32_e32 v201, v137, v169
	v_fmac_f32_e32 v202, v138, v170
	v_fmac_f32_e32 v203, v139, v171
	v_fmac_f32_e32 v204, v140, v172
	v_fmac_f32_e32 v205, v141, v173
	v_fmac_f32_e32 v206, v142, v174
	v_fmac_f32_e32 v207, v143, v175
	v_fmac_f32_e32 v200, v144, v176
	v_fmac_f32_e32 v201, v145, v177
	v_fmac_f32_e32 v202, v146, v178
	v_fmac_f32_e32 v203, v147, v179
	v_fmac_f32_e32 v204, v148, v180
	v_fmac_f32_e32 v205, v149, v181
	v_fmac_f32_e32 v206, v150, v182
	v_fmac_f32_e32 v207, v151, v183
	v_fmac_f32_e32 v200, v152, v184
	v_fmac_f32_e32 v201, v153, v185
	v_fmac_f32_e32 v202, v154, v186
	v_fmac_f32_e32 v203, v155, v187
	v_fmac_f32_e32 v204, v156, v188
	v_fmac_f32_e32 v205, v157, v189
	v_fmac_f32_e32 v206, v158, v190
	v_fmac_f32_e32 v207, v159, v191
	v_cvt_pk_bf16_f32 v40, v200, v201
	v_cvt_pk_bf16_f32 v41, v202, v203
	v_cvt_pk_bf16_f32 v42, v204, v205
	v_cvt_pk_bf16_f32 v43, v206, v207
	global_store_dwordx4 v1, v[40:43], s[42:43]
	s_add_u32 s42, s42, 0x2000
	s_addc_u32 s43, s43, 0
	s_add_u32 s78, s78, 0x4000
	s_addc_u32 s79, s79, 0
	s_add_i32 s82, s82, 1
	s_add_u32 s32, s32, 1
	s_sub_u32 s2, s2, 1
	s_cmp_eq_u32 s2, 0
	s_cbranch_scc1 .Lp5_conv_next_item
	v_lshlrev_b32_e32 v192, 16, v76
	v_and_b32_e32 v193, 0xffff0000, v76
	v_lshlrev_b32_e32 v194, 16, v77
	v_and_b32_e32 v195, 0xffff0000, v77
	v_lshlrev_b32_e32 v196, 16, v78
	v_and_b32_e32 v197, 0xffff0000, v78
	v_lshlrev_b32_e32 v198, 16, v79
	v_and_b32_e32 v199, 0xffff0000, v79
	s_cmp_lt_i32 s82, 0
	s_cbranch_scc1 .Lp5_conv_nost_3
	global_store_dwordx4 v2, v[192:195], s[78:79]
	global_store_dwordx4 v2, v[196:199], s[78:79] offset:16
.Lp5_conv_nost_3:
	v_fma_f32 v200, v128, v168, v160
	v_fma_f32 v201, v129, v169, v161
	v_fma_f32 v202, v130, v170, v162
	v_fma_f32 v203, v131, v171, v163
	v_fma_f32 v204, v132, v172, v164
	v_fma_f32 v205, v133, v173, v165
	v_fma_f32 v206, v134, v174, v166
	v_fma_f32 v207, v135, v175, v167
	v_fmac_f32_e32 v200, v136, v176
	v_fmac_f32_e32 v201, v137, v177
	v_fmac_f32_e32 v202, v138, v178
	v_fmac_f32_e32 v203, v139, v179
	v_fmac_f32_e32 v204, v140, v180
	v_fmac_f32_e32 v205, v141, v181
	v_fmac_f32_e32 v206, v142, v182
	v_fmac_f32_e32 v207, v143, v183
	v_fmac_f32_e32 v200, v144, v184
	v_fmac_f32_e32 v201, v145, v185
	v_fmac_f32_e32 v202, v146, v186
	v_fmac_f32_e32 v203, v147, v187
	v_fmac_f32_e32 v204, v148, v188
	v_fmac_f32_e32 v205, v149, v189
	v_fmac_f32_e32 v206, v150, v190
	v_fmac_f32_e32 v207, v151, v191
	v_fmac_f32_e32 v200, v152, v192
	v_fmac_f32_e32 v201, v153, v193
	v_fmac_f32_e32 v202, v154, v194
	v_fmac_f32_e32 v203, v155, v195
	v_fmac_f32_e32 v204, v156, v196
	v_fmac_f32_e32 v205, v157, v197
	v_fmac_f32_e32 v206, v158, v198
	v_fmac_f32_e32 v207, v159, v199
	v_cvt_pk_bf16_f32 v44, v200, v201
	v_cvt_pk_bf16_f32 v45, v202, v203
	v_cvt_pk_bf16_f32 v46, v204, v205
	v_cvt_pk_bf16_f32 v47, v206, v207
	global_store_dwordx4 v1, v[44:47], s[42:43]
	s_add_u32 s42, s42, 0x2000
	s_addc_u32 s43, s43, 0
	s_add_u32 s78, s78, 0x4000
	s_addc_u32 s79, s79, 0
	s_add_i32 s82, s82, 1
	s_add_u32 s32, s32, 1
	s_sub_u32 s2, s2, 1
	s_cmp_eq_u32 s2, 0
	s_cbranch_scc1 .Lp5_conv_next_item
	v_lshlrev_b32_e32 v168, 16, v80
	v_and_b32_e32 v169, 0xffff0000, v80
	v_lshlrev_b32_e32 v170, 16, v81
	v_and_b32_e32 v171, 0xffff0000, v81
	v_lshlrev_b32_e32 v172, 16, v82
	v_and_b32_e32 v173, 0xffff0000, v82
	v_lshlrev_b32_e32 v174, 16, v83
	v_and_b32_e32 v175, 0xffff0000, v83
	s_cmp_lt_i32 s82, 0
	s_cbranch_scc1 .Lp5_conv_nost_4
	global_store_dwordx4 v2, v[168:171], s[78:79]
	global_store_dwordx4 v2, v[172:175], s[78:79] offset:16
.Lp5_conv_nost_4:
	v_fma_f32 v200, v128, v176, v160
	v_fma_f32 v201, v129, v177, v161
	v_fma_f32 v202, v130, v178, v162
	v_fma_f32 v203, v131, v179, v163
	v_fma_f32 v204, v132, v180, v164
	v_fma_f32 v205, v133, v181, v165
	v_fma_f32 v206, v134, v182, v166
	v_fma_f32 v207, v135, v183, v167
	v_fmac_f32_e32 v200, v136, v184
	v_fmac_f32_e32 v201, v137, v185
	v_fmac_f32_e32 v202, v138, v186
	v_fmac_f32_e32 v203, v139, v187
	v_fmac_f32_e32 v204, v140, v188
	v_fmac_f32_e32 v205, v141, v189
	v_fmac_f32_e32 v206, v142, v190
	v_fmac_f32_e32 v207, v143, v191
	v_fmac_f32_e32 v200, v144, v192
	v_fmac_f32_e32 v201, v145, v193
	v_fmac_f32_e32 v202, v146, v194
	v_fmac_f32_e32 v203, v147, v195
	v_fmac_f32_e32 v204, v148, v196
	v_fmac_f32_e32 v205, v149, v197
	v_fmac_f32_e32 v206, v150, v198
	v_fmac_f32_e32 v207, v151, v199
	v_fmac_f32_e32 v200, v152, v168
	v_fmac_f32_e32 v201, v153, v169
	v_fmac_f32_e32 v202, v154, v170
	v_fmac_f32_e32 v203, v155, v171
	v_fmac_f32_e32 v204, v156, v172
	v_fmac_f32_e32 v205, v157, v173
	v_fmac_f32_e32 v206, v158, v174
	v_fmac_f32_e32 v207, v159, v175
	v_cvt_pk_bf16_f32 v40, v200, v201
	v_cvt_pk_bf16_f32 v41, v202, v203
	v_cvt_pk_bf16_f32 v42, v204, v205
	v_cvt_pk_bf16_f32 v43, v206, v207
	global_store_dwordx4 v1, v[40:43], s[42:43]
	s_add_u32 s42, s42, 0x2000
	s_addc_u32 s43, s43, 0
	s_add_u32 s78, s78, 0x4000
	s_addc_u32 s79, s79, 0
	s_add_i32 s82, s82, 1
	s_add_u32 s32, s32, 1
	s_sub_u32 s2, s2, 1
	s_cmp_eq_u32 s2, 0
	s_cbranch_scc1 .Lp5_conv_next_item
	v_lshlrev_b32_e32 v176, 16, v84
	v_and_b32_e32 v177, 0xffff0000, v84
	v_lshlrev_b32_e32 v178, 16, v85
	v_and_b32_e32 v179, 0xffff0000, v85
	v_lshlrev_b32_e32 v180, 16, v86
	v_and_b32_e32 v181, 0xffff0000, v86
	v_lshlrev_b32_e32 v182, 16, v87
	v_and_b32_e32 v183, 0xffff0000, v87
	s_cmp_lt_i32 s82, 0
	s_cbranch_scc1 .Lp5_conv_nost_5
	global_store_dwordx4 v2, v[176:179], s[78:79]
	global_store_dwordx4 v2, v[180:183], s[78:79] offset:16
.Lp5_conv_nost_5:
	v_fma_f32 v200, v128, v184, v160
	v_fma_f32 v201, v129, v185, v161
	v_fma_f32 v202, v130, v186, v162
	v_fma_f32 v203, v131, v187, v163
	v_fma_f32 v204, v132, v188, v164
	v_fma_f32 v205, v133, v189, v165
	v_fma_f32 v206, v134, v190, v166
	v_fma_f32 v207, v135, v191, v167
	v_fmac_f32_e32 v200, v136, v192
	v_fmac_f32_e32 v201, v137, v193
	v_fmac_f32_e32 v202, v138, v194
	v_fmac_f32_e32 v203, v139, v195
	v_fmac_f32_e32 v204, v140, v196
	v_fmac_f32_e32 v205, v141, v197
	v_fmac_f32_e32 v206, v142, v198
	v_fmac_f32_e32 v207, v143, v199
	v_fmac_f32_e32 v200, v144, v168
	v_fmac_f32_e32 v201, v145, v169
	v_fmac_f32_e32 v202, v146, v170
	v_fmac_f32_e32 v203, v147, v171
	v_fmac_f32_e32 v204, v148, v172
	v_fmac_f32_e32 v205, v149, v173
	v_fmac_f32_e32 v206, v150, v174
	v_fmac_f32_e32 v207, v151, v175
	v_fmac_f32_e32 v200, v152, v176
	v_fmac_f32_e32 v201, v153, v177
	v_fmac_f32_e32 v202, v154, v178
	v_fmac_f32_e32 v203, v155, v179
	v_fmac_f32_e32 v204, v156, v180
	v_fmac_f32_e32 v205, v157, v181
	v_fmac_f32_e32 v206, v158, v182
	v_fmac_f32_e32 v207, v159, v183
	v_cvt_pk_bf16_f32 v44, v200, v201
	v_cvt_pk_bf16_f32 v45, v202, v203
	v_cvt_pk_bf16_f32 v46, v204, v205
	v_cvt_pk_bf16_f32 v47, v206, v207
	global_store_dwordx4 v1, v[44:47], s[42:43]
	s_add_u32 s42, s42, 0x2000
	s_addc_u32 s43, s43, 0
	s_add_u32 s78, s78, 0x4000
	s_addc_u32 s79, s79, 0
	s_add_i32 s82, s82, 1
	s_add_u32 s32, s32, 1
	s_sub_u32 s2, s2, 1
	s_cmp_eq_u32 s2, 0
	s_cbranch_scc1 .Lp5_conv_next_item
	v_lshlrev_b32_e32 v184, 16, v88
	v_and_b32_e32 v185, 0xffff0000, v88
	v_lshlrev_b32_e32 v186, 16, v89
	v_and_b32_e32 v187, 0xffff0000, v89
	v_lshlrev_b32_e32 v188, 16, v90
	v_and_b32_e32 v189, 0xffff0000, v90
	v_lshlrev_b32_e32 v190, 16, v91
	v_and_b32_e32 v191, 0xffff0000, v91
	s_cmp_lt_i32 s82, 0
	s_cbranch_scc1 .Lp5_conv_nost_6
	global_store_dwordx4 v2, v[184:187], s[78:79]
	global_store_dwordx4 v2, v[188:191], s[78:79] offset:16
.Lp5_conv_nost_6:
	v_fma_f32 v200, v128, v192, v160
	v_fma_f32 v201, v129, v193, v161
	v_fma_f32 v202, v130, v194, v162
	v_fma_f32 v203, v131, v195, v163
	v_fma_f32 v204, v132, v196, v164
	v_fma_f32 v205, v133, v197, v165
	v_fma_f32 v206, v134, v198, v166
	v_fma_f32 v207, v135, v199, v167
	v_fmac_f32_e32 v200, v136, v168
	v_fmac_f32_e32 v201, v137, v169
	v_fmac_f32_e32 v202, v138, v170
	v_fmac_f32_e32 v203, v139, v171
	v_fmac_f32_e32 v204, v140, v172
	v_fmac_f32_e32 v205, v141, v173
	v_fmac_f32_e32 v206, v142, v174
	v_fmac_f32_e32 v207, v143, v175
	v_fmac_f32_e32 v200, v144, v176
	v_fmac_f32_e32 v201, v145, v177
	v_fmac_f32_e32 v202, v146, v178
	v_fmac_f32_e32 v203, v147, v179
	v_fmac_f32_e32 v204, v148, v180
	v_fmac_f32_e32 v205, v149, v181
	v_fmac_f32_e32 v206, v150, v182
	v_fmac_f32_e32 v207, v151, v183
	v_fmac_f32_e32 v200, v152, v184
	v_fmac_f32_e32 v201, v153, v185
	v_fmac_f32_e32 v202, v154, v186
	v_fmac_f32_e32 v203, v155, v187
	v_fmac_f32_e32 v204, v156, v188
	v_fmac_f32_e32 v205, v157, v189
	v_fmac_f32_e32 v206, v158, v190
	v_fmac_f32_e32 v207, v159, v191
	v_cvt_pk_bf16_f32 v40, v200, v201
	v_cvt_pk_bf16_f32 v41, v202, v203
	v_cvt_pk_bf16_f32 v42, v204, v205
	v_cvt_pk_bf16_f32 v43, v206, v207
	global_store_dwordx4 v1, v[40:43], s[42:43]
	s_add_u32 s42, s42, 0x2000
	s_addc_u32 s43, s43, 0
	s_add_u32 s78, s78, 0x4000
	s_addc_u32 s79, s79, 0
	s_add_i32 s82, s82, 1
	s_add_u32 s32, s32, 1
	s_sub_u32 s2, s2, 1
	s_cmp_eq_u32 s2, 0
	s_cbranch_scc1 .Lp5_conv_next_item
	v_lshlrev_b32_e32 v192, 16, v92
	v_and_b32_e32 v193, 0xffff0000, v92
	v_lshlrev_b32_e32 v194, 16, v93
	v_and_b32_e32 v195, 0xffff0000, v93
	v_lshlrev_b32_e32 v196, 16, v94
	v_and_b32_e32 v197, 0xffff0000, v94
	v_lshlrev_b32_e32 v198, 16, v95
	v_and_b32_e32 v199, 0xffff0000, v95
	s_cmp_lt_i32 s82, 0
	s_cbranch_scc1 .Lp5_conv_nost_7
	global_store_dwordx4 v2, v[192:195], s[78:79]
	global_store_dwordx4 v2, v[196:199], s[78:79] offset:16
.Lp5_conv_nost_7:
	v_fma_f32 v200, v128, v168, v160
	v_fma_f32 v201, v129, v169, v161
	v_fma_f32 v202, v130, v170, v162
	v_fma_f32 v203, v131, v171, v163
	v_fma_f32 v204, v132, v172, v164
	v_fma_f32 v205, v133, v173, v165
	v_fma_f32 v206, v134, v174, v166
	v_fma_f32 v207, v135, v175, v167
	v_fmac_f32_e32 v200, v136, v176
	v_fmac_f32_e32 v201, v137, v177
	v_fmac_f32_e32 v202, v138, v178
	v_fmac_f32_e32 v203, v139, v179
	v_fmac_f32_e32 v204, v140, v180
	v_fmac_f32_e32 v205, v141, v181
	v_fmac_f32_e32 v206, v142, v182
	v_fmac_f32_e32 v207, v143, v183
	v_fmac_f32_e32 v200, v144, v184
	v_fmac_f32_e32 v201, v145, v185
	v_fmac_f32_e32 v202, v146, v186
	v_fmac_f32_e32 v203, v147, v187
	v_fmac_f32_e32 v204, v148, v188
	v_fmac_f32_e32 v205, v149, v189
	v_fmac_f32_e32 v206, v150, v190
	v_fmac_f32_e32 v207, v151, v191
	v_fmac_f32_e32 v200, v152, v192
	v_fmac_f32_e32 v201, v153, v193
	v_fmac_f32_e32 v202, v154, v194
	v_fmac_f32_e32 v203, v155, v195
	v_fmac_f32_e32 v204, v156, v196
	v_fmac_f32_e32 v205, v157, v197
	v_fmac_f32_e32 v206, v158, v198
	v_fmac_f32_e32 v207, v159, v199
	v_cvt_pk_bf16_f32 v44, v200, v201
	v_cvt_pk_bf16_f32 v45, v202, v203
	v_cvt_pk_bf16_f32 v46, v204, v205
	v_cvt_pk_bf16_f32 v47, v206, v207
	global_store_dwordx4 v1, v[44:47], s[42:43]
	s_add_u32 s42, s42, 0x2000
	s_addc_u32 s43, s43, 0
	s_add_u32 s78, s78, 0x4000
	s_addc_u32 s79, s79, 0
	s_add_i32 s82, s82, 1
	s_add_u32 s32, s32, 1
	s_sub_u32 s2, s2, 1
	s_cmp_eq_u32 s2, 0
	s_cbranch_scc1 .Lp5_conv_next_item
	v_lshlrev_b32_e32 v168, 16, v96
	v_and_b32_e32 v169, 0xffff0000, v96
	v_lshlrev_b32_e32 v170, 16, v97
	v_and_b32_e32 v171, 0xffff0000, v97
	v_lshlrev_b32_e32 v172, 16, v98
	v_and_b32_e32 v173, 0xffff0000, v98
	v_lshlrev_b32_e32 v174, 16, v99
	v_and_b32_e32 v175, 0xffff0000, v99
	s_cmp_lt_i32 s82, 0
	s_cbranch_scc1 .Lp5_conv_nost_8
	global_store_dwordx4 v2, v[168:171], s[78:79]
	global_store_dwordx4 v2, v[172:175], s[78:79] offset:16
.Lp5_conv_nost_8:
	v_fma_f32 v200, v128, v176, v160
	v_fma_f32 v201, v129, v177, v161
	v_fma_f32 v202, v130, v178, v162
	v_fma_f32 v203, v131, v179, v163
	v_fma_f32 v204, v132, v180, v164
	v_fma_f32 v205, v133, v181, v165
	v_fma_f32 v206, v134, v182, v166
	v_fma_f32 v207, v135, v183, v167
	v_fmac_f32_e32 v200, v136, v184
	v_fmac_f32_e32 v201, v137, v185
	v_fmac_f32_e32 v202, v138, v186
	v_fmac_f32_e32 v203, v139, v187
	v_fmac_f32_e32 v204, v140, v188
	v_fmac_f32_e32 v205, v141, v189
	v_fmac_f32_e32 v206, v142, v190
	v_fmac_f32_e32 v207, v143, v191
	v_fmac_f32_e32 v200, v144, v192
	v_fmac_f32_e32 v201, v145, v193
	v_fmac_f32_e32 v202, v146, v194
	v_fmac_f32_e32 v203, v147, v195
	v_fmac_f32_e32 v204, v148, v196
	v_fmac_f32_e32 v205, v149, v197
	v_fmac_f32_e32 v206, v150, v198
	v_fmac_f32_e32 v207, v151, v199
	v_fmac_f32_e32 v200, v152, v168
	v_fmac_f32_e32 v201, v153, v169
	v_fmac_f32_e32 v202, v154, v170
	v_fmac_f32_e32 v203, v155, v171
	v_fmac_f32_e32 v204, v156, v172
	v_fmac_f32_e32 v205, v157, v173
	v_fmac_f32_e32 v206, v158, v174
	v_fmac_f32_e32 v207, v159, v175
	v_cvt_pk_bf16_f32 v40, v200, v201
	v_cvt_pk_bf16_f32 v41, v202, v203
	v_cvt_pk_bf16_f32 v42, v204, v205
	v_cvt_pk_bf16_f32 v43, v206, v207
	global_store_dwordx4 v1, v[40:43], s[42:43]
	s_add_u32 s42, s42, 0x2000
	s_addc_u32 s43, s43, 0
	s_add_u32 s78, s78, 0x4000
	s_addc_u32 s79, s79, 0
	s_add_i32 s82, s82, 1
	s_add_u32 s32, s32, 1
	s_sub_u32 s2, s2, 1
	s_cmp_eq_u32 s2, 0
	s_cbranch_scc1 .Lp5_conv_next_item
	v_lshlrev_b32_e32 v176, 16, v100
	v_and_b32_e32 v177, 0xffff0000, v100
	v_lshlrev_b32_e32 v178, 16, v101
	v_and_b32_e32 v179, 0xffff0000, v101
	v_lshlrev_b32_e32 v180, 16, v102
	v_and_b32_e32 v181, 0xffff0000, v102
	v_lshlrev_b32_e32 v182, 16, v103
	v_and_b32_e32 v183, 0xffff0000, v103
	s_cmp_lt_i32 s82, 0
	s_cbranch_scc1 .Lp5_conv_nost_9
	global_store_dwordx4 v2, v[176:179], s[78:79]
	global_store_dwordx4 v2, v[180:183], s[78:79] offset:16
.Lp5_conv_nost_9:
	v_fma_f32 v200, v128, v184, v160
	v_fma_f32 v201, v129, v185, v161
	v_fma_f32 v202, v130, v186, v162
	v_fma_f32 v203, v131, v187, v163
	v_fma_f32 v204, v132, v188, v164
	v_fma_f32 v205, v133, v189, v165
	v_fma_f32 v206, v134, v190, v166
	v_fma_f32 v207, v135, v191, v167
	v_fmac_f32_e32 v200, v136, v192
	v_fmac_f32_e32 v201, v137, v193
	v_fmac_f32_e32 v202, v138, v194
	v_fmac_f32_e32 v203, v139, v195
	v_fmac_f32_e32 v204, v140, v196
	v_fmac_f32_e32 v205, v141, v197
	v_fmac_f32_e32 v206, v142, v198
	v_fmac_f32_e32 v207, v143, v199
	v_fmac_f32_e32 v200, v144, v168
	v_fmac_f32_e32 v201, v145, v169
	v_fmac_f32_e32 v202, v146, v170
	v_fmac_f32_e32 v203, v147, v171
	v_fmac_f32_e32 v204, v148, v172
	v_fmac_f32_e32 v205, v149, v173
	v_fmac_f32_e32 v206, v150, v174
	v_fmac_f32_e32 v207, v151, v175
	v_fmac_f32_e32 v200, v152, v176
	v_fmac_f32_e32 v201, v153, v177
	v_fmac_f32_e32 v202, v154, v178
	v_fmac_f32_e32 v203, v155, v179
	v_fmac_f32_e32 v204, v156, v180
	v_fmac_f32_e32 v205, v157, v181
	v_fmac_f32_e32 v206, v158, v182
	v_fmac_f32_e32 v207, v159, v183
	v_cvt_pk_bf16_f32 v44, v200, v201
	v_cvt_pk_bf16_f32 v45, v202, v203
	v_cvt_pk_bf16_f32 v46, v204, v205
	v_cvt_pk_bf16_f32 v47, v206, v207
	global_store_dwordx4 v1, v[44:47], s[42:43]
	s_add_u32 s42, s42, 0x2000
	s_addc_u32 s43, s43, 0
	s_add_u32 s78, s78, 0x4000
	s_addc_u32 s79, s79, 0
	s_add_i32 s82, s82, 1
	s_add_u32 s32, s32, 1
	s_sub_u32 s2, s2, 1
	s_cmp_eq_u32 s2, 0
	s_cbranch_scc1 .Lp5_conv_next_item
	v_lshlrev_b32_e32 v184, 16, v104
	v_and_b32_e32 v185, 0xffff0000, v104
	v_lshlrev_b32_e32 v186, 16, v105
	v_and_b32_e32 v187, 0xffff0000, v105
	v_lshlrev_b32_e32 v188, 16, v106
	v_and_b32_e32 v189, 0xffff0000, v106
	v_lshlrev_b32_e32 v190, 16, v107
	v_and_b32_e32 v191, 0xffff0000, v107
	s_cmp_lt_i32 s82, 0
	s_cbranch_scc1 .Lp5_conv_nost_10
	global_store_dwordx4 v2, v[184:187], s[78:79]
	global_store_dwordx4 v2, v[188:191], s[78:79] offset:16
.Lp5_conv_nost_10:
	v_fma_f32 v200, v128, v192, v160
	v_fma_f32 v201, v129, v193, v161
	v_fma_f32 v202, v130, v194, v162
	v_fma_f32 v203, v131, v195, v163
	v_fma_f32 v204, v132, v196, v164
	v_fma_f32 v205, v133, v197, v165
	v_fma_f32 v206, v134, v198, v166
	v_fma_f32 v207, v135, v199, v167
	v_fmac_f32_e32 v200, v136, v168
	v_fmac_f32_e32 v201, v137, v169
	v_fmac_f32_e32 v202, v138, v170
	v_fmac_f32_e32 v203, v139, v171
	v_fmac_f32_e32 v204, v140, v172
	v_fmac_f32_e32 v205, v141, v173
	v_fmac_f32_e32 v206, v142, v174
	v_fmac_f32_e32 v207, v143, v175
	v_fmac_f32_e32 v200, v144, v176
	v_fmac_f32_e32 v201, v145, v177
	v_fmac_f32_e32 v202, v146, v178
	v_fmac_f32_e32 v203, v147, v179
	v_fmac_f32_e32 v204, v148, v180
	v_fmac_f32_e32 v205, v149, v181
	v_fmac_f32_e32 v206, v150, v182
	v_fmac_f32_e32 v207, v151, v183
	v_fmac_f32_e32 v200, v152, v184
	v_fmac_f32_e32 v201, v153, v185
	v_fmac_f32_e32 v202, v154, v186
	v_fmac_f32_e32 v203, v155, v187
	v_fmac_f32_e32 v204, v156, v188
	v_fmac_f32_e32 v205, v157, v189
	v_fmac_f32_e32 v206, v158, v190
	v_fmac_f32_e32 v207, v159, v191
	v_cvt_pk_bf16_f32 v40, v200, v201
	v_cvt_pk_bf16_f32 v41, v202, v203
	v_cvt_pk_bf16_f32 v42, v204, v205
	v_cvt_pk_bf16_f32 v43, v206, v207
	global_store_dwordx4 v1, v[40:43], s[42:43]
	s_add_u32 s42, s42, 0x2000
	s_addc_u32 s43, s43, 0
	s_add_u32 s78, s78, 0x4000
	s_addc_u32 s79, s79, 0
	s_add_i32 s82, s82, 1
	s_add_u32 s32, s32, 1
	s_sub_u32 s2, s2, 1
	s_cmp_eq_u32 s2, 0
	s_cbranch_scc1 .Lp5_conv_next_item
	v_lshlrev_b32_e32 v192, 16, v108
	v_and_b32_e32 v193, 0xffff0000, v108
	v_lshlrev_b32_e32 v194, 16, v109
	v_and_b32_e32 v195, 0xffff0000, v109
	v_lshlrev_b32_e32 v196, 16, v110
	v_and_b32_e32 v197, 0xffff0000, v110
	v_lshlrev_b32_e32 v198, 16, v111
	v_and_b32_e32 v199, 0xffff0000, v111
	s_cmp_lt_i32 s82, 0
	s_cbranch_scc1 .Lp5_conv_nost_11
	global_store_dwordx4 v2, v[192:195], s[78:79]
	global_store_dwordx4 v2, v[196:199], s[78:79] offset:16
.Lp5_conv_nost_11:
	v_fma_f32 v200, v128, v168, v160
	v_fma_f32 v201, v129, v169, v161
	v_fma_f32 v202, v130, v170, v162
	v_fma_f32 v203, v131, v171, v163
	v_fma_f32 v204, v132, v172, v164
	v_fma_f32 v205, v133, v173, v165
	v_fma_f32 v206, v134, v174, v166
	v_fma_f32 v207, v135, v175, v167
	v_fmac_f32_e32 v200, v136, v176
	v_fmac_f32_e32 v201, v137, v177
	v_fmac_f32_e32 v202, v138, v178
	v_fmac_f32_e32 v203, v139, v179
	v_fmac_f32_e32 v204, v140, v180
	v_fmac_f32_e32 v205, v141, v181
	v_fmac_f32_e32 v206, v142, v182
	v_fmac_f32_e32 v207, v143, v183
	v_fmac_f32_e32 v200, v144, v184
	v_fmac_f32_e32 v201, v145, v185
	v_fmac_f32_e32 v202, v146, v186
	v_fmac_f32_e32 v203, v147, v187
	v_fmac_f32_e32 v204, v148, v188
	v_fmac_f32_e32 v205, v149, v189
	v_fmac_f32_e32 v206, v150, v190
	v_fmac_f32_e32 v207, v151, v191
	v_fmac_f32_e32 v200, v152, v192
	v_fmac_f32_e32 v201, v153, v193
	v_fmac_f32_e32 v202, v154, v194
	v_fmac_f32_e32 v203, v155, v195
	v_fmac_f32_e32 v204, v156, v196
	v_fmac_f32_e32 v205, v157, v197
	v_fmac_f32_e32 v206, v158, v198
	v_fmac_f32_e32 v207, v159, v199
	v_cvt_pk_bf16_f32 v44, v200, v201
	v_cvt_pk_bf16_f32 v45, v202, v203
	v_cvt_pk_bf16_f32 v46, v204, v205
	v_cvt_pk_bf16_f32 v47, v206, v207
	global_store_dwordx4 v1, v[44:47], s[42:43]
	s_add_u32 s42, s42, 0x2000
	s_addc_u32 s43, s43, 0
	s_add_u32 s78, s78, 0x4000
	s_addc_u32 s79, s79, 0
	s_add_i32 s82, s82, 1
	s_add_u32 s32, s32, 1
	s_sub_u32 s2, s2, 1
	s_cmp_eq_u32 s2, 0
	s_cbranch_scc1 .Lp5_conv_next_item
	v_lshlrev_b32_e32 v168, 16, v112
	v_and_b32_e32 v169, 0xffff0000, v112
	v_lshlrev_b32_e32 v170, 16, v113
	v_and_b32_e32 v171, 0xffff0000, v113
	v_lshlrev_b32_e32 v172, 16, v114
	v_and_b32_e32 v173, 0xffff0000, v114
	v_lshlrev_b32_e32 v174, 16, v115
	v_and_b32_e32 v175, 0xffff0000, v115
	s_cmp_lt_i32 s82, 0
	s_cbranch_scc1 .Lp5_conv_nost_12
	global_store_dwordx4 v2, v[168:171], s[78:79]
	global_store_dwordx4 v2, v[172:175], s[78:79] offset:16
.Lp5_conv_nost_12:
	v_fma_f32 v200, v128, v176, v160
	v_fma_f32 v201, v129, v177, v161
	v_fma_f32 v202, v130, v178, v162
	v_fma_f32 v203, v131, v179, v163
	v_fma_f32 v204, v132, v180, v164
	v_fma_f32 v205, v133, v181, v165
	v_fma_f32 v206, v134, v182, v166
	v_fma_f32 v207, v135, v183, v167
	v_fmac_f32_e32 v200, v136, v184
	v_fmac_f32_e32 v201, v137, v185
	v_fmac_f32_e32 v202, v138, v186
	v_fmac_f32_e32 v203, v139, v187
	v_fmac_f32_e32 v204, v140, v188
	v_fmac_f32_e32 v205, v141, v189
	v_fmac_f32_e32 v206, v142, v190
	v_fmac_f32_e32 v207, v143, v191
	v_fmac_f32_e32 v200, v144, v192
	v_fmac_f32_e32 v201, v145, v193
	v_fmac_f32_e32 v202, v146, v194
	v_fmac_f32_e32 v203, v147, v195
	v_fmac_f32_e32 v204, v148, v196
	v_fmac_f32_e32 v205, v149, v197
	v_fmac_f32_e32 v206, v150, v198
	v_fmac_f32_e32 v207, v151, v199
	v_fmac_f32_e32 v200, v152, v168
	v_fmac_f32_e32 v201, v153, v169
	v_fmac_f32_e32 v202, v154, v170
	v_fmac_f32_e32 v203, v155, v171
	v_fmac_f32_e32 v204, v156, v172
	v_fmac_f32_e32 v205, v157, v173
	v_fmac_f32_e32 v206, v158, v174
	v_fmac_f32_e32 v207, v159, v175
	v_cvt_pk_bf16_f32 v40, v200, v201
	v_cvt_pk_bf16_f32 v41, v202, v203
	v_cvt_pk_bf16_f32 v42, v204, v205
	v_cvt_pk_bf16_f32 v43, v206, v207
	global_store_dwordx4 v1, v[40:43], s[42:43]
	s_add_u32 s42, s42, 0x2000
	s_addc_u32 s43, s43, 0
	s_add_u32 s78, s78, 0x4000
	s_addc_u32 s79, s79, 0
	s_add_i32 s82, s82, 1
	s_add_u32 s32, s32, 1
	s_sub_u32 s2, s2, 1
	s_cmp_eq_u32 s2, 0
	s_cbranch_scc1 .Lp5_conv_next_item
	v_lshlrev_b32_e32 v176, 16, v116
	v_and_b32_e32 v177, 0xffff0000, v116
	v_lshlrev_b32_e32 v178, 16, v117
	v_and_b32_e32 v179, 0xffff0000, v117
	v_lshlrev_b32_e32 v180, 16, v118
	v_and_b32_e32 v181, 0xffff0000, v118
	v_lshlrev_b32_e32 v182, 16, v119
	v_and_b32_e32 v183, 0xffff0000, v119
	s_cmp_lt_i32 s82, 0
	s_cbranch_scc1 .Lp5_conv_nost_13
	global_store_dwordx4 v2, v[176:179], s[78:79]
	global_store_dwordx4 v2, v[180:183], s[78:79] offset:16
.Lp5_conv_nost_13:
	v_fma_f32 v200, v128, v184, v160
	v_fma_f32 v201, v129, v185, v161
	v_fma_f32 v202, v130, v186, v162
	v_fma_f32 v203, v131, v187, v163
	v_fma_f32 v204, v132, v188, v164
	v_fma_f32 v205, v133, v189, v165
	v_fma_f32 v206, v134, v190, v166
	v_fma_f32 v207, v135, v191, v167
	v_fmac_f32_e32 v200, v136, v192
	v_fmac_f32_e32 v201, v137, v193
	v_fmac_f32_e32 v202, v138, v194
	v_fmac_f32_e32 v203, v139, v195
	v_fmac_f32_e32 v204, v140, v196
	v_fmac_f32_e32 v205, v141, v197
	v_fmac_f32_e32 v206, v142, v198
	v_fmac_f32_e32 v207, v143, v199
	v_fmac_f32_e32 v200, v144, v168
	v_fmac_f32_e32 v201, v145, v169
	v_fmac_f32_e32 v202, v146, v170
	v_fmac_f32_e32 v203, v147, v171
	v_fmac_f32_e32 v204, v148, v172
	v_fmac_f32_e32 v205, v149, v173
	v_fmac_f32_e32 v206, v150, v174
	v_fmac_f32_e32 v207, v151, v175
	v_fmac_f32_e32 v200, v152, v176
	v_fmac_f32_e32 v201, v153, v177
	v_fmac_f32_e32 v202, v154, v178
	v_fmac_f32_e32 v203, v155, v179
	v_fmac_f32_e32 v204, v156, v180
	v_fmac_f32_e32 v205, v157, v181
	v_fmac_f32_e32 v206, v158, v182
	v_fmac_f32_e32 v207, v159, v183
	v_cvt_pk_bf16_f32 v44, v200, v201
	v_cvt_pk_bf16_f32 v45, v202, v203
	v_cvt_pk_bf16_f32 v46, v204, v205
	v_cvt_pk_bf16_f32 v47, v206, v207
	global_store_dwordx4 v1, v[44:47], s[42:43]
	s_add_u32 s42, s42, 0x2000
	s_addc_u32 s43, s43, 0
	s_add_u32 s78, s78, 0x4000
	s_addc_u32 s79, s79, 0
	s_add_i32 s82, s82, 1
	s_add_u32 s32, s32, 1
	s_sub_u32 s2, s2, 1
	s_cmp_eq_u32 s2, 0
	s_cbranch_scc1 .Lp5_conv_next_item
	v_lshlrev_b32_e32 v184, 16, v120
	v_and_b32_e32 v185, 0xffff0000, v120
	v_lshlrev_b32_e32 v186, 16, v121
	v_and_b32_e32 v187, 0xffff0000, v121
	v_lshlrev_b32_e32 v188, 16, v122
	v_and_b32_e32 v189, 0xffff0000, v122
	v_lshlrev_b32_e32 v190, 16, v123
	v_and_b32_e32 v191, 0xffff0000, v123
	s_cmp_lt_i32 s82, 0
	s_cbranch_scc1 .Lp5_conv_nost_14
	global_store_dwordx4 v2, v[184:187], s[78:79]
	global_store_dwordx4 v2, v[188:191], s[78:79] offset:16
.Lp5_conv_nost_14:
	v_fma_f32 v200, v128, v192, v160
	v_fma_f32 v201, v129, v193, v161
	v_fma_f32 v202, v130, v194, v162
	v_fma_f32 v203, v131, v195, v163
	v_fma_f32 v204, v132, v196, v164
	v_fma_f32 v205, v133, v197, v165
	v_fma_f32 v206, v134, v198, v166
	v_fma_f32 v207, v135, v199, v167
	v_fmac_f32_e32 v200, v136, v168
	v_fmac_f32_e32 v201, v137, v169
	v_fmac_f32_e32 v202, v138, v170
	v_fmac_f32_e32 v203, v139, v171
	v_fmac_f32_e32 v204, v140, v172
	v_fmac_f32_e32 v205, v141, v173
	v_fmac_f32_e32 v206, v142, v174
	v_fmac_f32_e32 v207, v143, v175
	v_fmac_f32_e32 v200, v144, v176
	v_fmac_f32_e32 v201, v145, v177
	v_fmac_f32_e32 v202, v146, v178
	v_fmac_f32_e32 v203, v147, v179
	v_fmac_f32_e32 v204, v148, v180
	v_fmac_f32_e32 v205, v149, v181
	v_fmac_f32_e32 v206, v150, v182
	v_fmac_f32_e32 v207, v151, v183
	v_fmac_f32_e32 v200, v152, v184
	v_fmac_f32_e32 v201, v153, v185
	v_fmac_f32_e32 v202, v154, v186
	v_fmac_f32_e32 v203, v155, v187
	v_fmac_f32_e32 v204, v156, v188
	v_fmac_f32_e32 v205, v157, v189
	v_fmac_f32_e32 v206, v158, v190
	v_fmac_f32_e32 v207, v159, v191
	v_cvt_pk_bf16_f32 v40, v200, v201
	v_cvt_pk_bf16_f32 v41, v202, v203
	v_cvt_pk_bf16_f32 v42, v204, v205
	v_cvt_pk_bf16_f32 v43, v206, v207
	global_store_dwordx4 v1, v[40:43], s[42:43]
	s_add_u32 s42, s42, 0x2000
	s_addc_u32 s43, s43, 0
	s_add_u32 s78, s78, 0x4000
	s_addc_u32 s79, s79, 0
	s_add_i32 s82, s82, 1
	s_add_u32 s32, s32, 1
	s_sub_u32 s2, s2, 1
	s_cmp_eq_u32 s2, 0
	s_cbranch_scc1 .Lp5_conv_next_item
	v_lshlrev_b32_e32 v192, 16, v124
	v_and_b32_e32 v193, 0xffff0000, v124
	v_lshlrev_b32_e32 v194, 16, v125
	v_and_b32_e32 v195, 0xffff0000, v125
	v_lshlrev_b32_e32 v196, 16, v126
	v_and_b32_e32 v197, 0xffff0000, v126
	v_lshlrev_b32_e32 v198, 16, v127
	v_and_b32_e32 v199, 0xffff0000, v127
	s_cmp_lt_i32 s82, 0
	s_cbranch_scc1 .Lp5_conv_nost_15
	global_store_dwordx4 v2, v[192:195], s[78:79]
	global_store_dwordx4 v2, v[196:199], s[78:79] offset:16
.Lp5_conv_nost_15:
	v_fma_f32 v200, v128, v168, v160
	v_fma_f32 v201, v129, v169, v161
	v_fma_f32 v202, v130, v170, v162
	v_fma_f32 v203, v131, v171, v163
	v_fma_f32 v204, v132, v172, v164
	v_fma_f32 v205, v133, v173, v165
	v_fma_f32 v206, v134, v174, v166
	v_fma_f32 v207, v135, v175, v167
	v_fmac_f32_e32 v200, v136, v176
	v_fmac_f32_e32 v201, v137, v177
	v_fmac_f32_e32 v202, v138, v178
	v_fmac_f32_e32 v203, v139, v179
	v_fmac_f32_e32 v204, v140, v180
	v_fmac_f32_e32 v205, v141, v181
	v_fmac_f32_e32 v206, v142, v182
	v_fmac_f32_e32 v207, v143, v183
	v_fmac_f32_e32 v200, v144, v184
	v_fmac_f32_e32 v201, v145, v185
	v_fmac_f32_e32 v202, v146, v186
	v_fmac_f32_e32 v203, v147, v187
	v_fmac_f32_e32 v204, v148, v188
	v_fmac_f32_e32 v205, v149, v189
	v_fmac_f32_e32 v206, v150, v190
	v_fmac_f32_e32 v207, v151, v191
	v_fmac_f32_e32 v200, v152, v192
	v_fmac_f32_e32 v201, v153, v193
	v_fmac_f32_e32 v202, v154, v194
	v_fmac_f32_e32 v203, v155, v195
	v_fmac_f32_e32 v204, v156, v196
	v_fmac_f32_e32 v205, v157, v197
	v_fmac_f32_e32 v206, v158, v198
	v_fmac_f32_e32 v207, v159, v199
	v_cvt_pk_bf16_f32 v44, v200, v201
	v_cvt_pk_bf16_f32 v45, v202, v203
	v_cvt_pk_bf16_f32 v46, v204, v205
	v_cvt_pk_bf16_f32 v47, v206, v207
	global_store_dwordx4 v1, v[44:47], s[42:43]
	s_add_u32 s42, s42, 0x2000
	s_addc_u32 s43, s43, 0
	s_add_u32 s78, s78, 0x4000
	s_addc_u32 s79, s79, 0
	s_add_i32 s82, s82, 1
	s_add_u32 s32, s32, 1
	s_sub_u32 s2, s2, 1
	s_add_u32 s61, s61, 1
	s_cmp_lg_u32 s2, 0
	s_cbranch_scc1 .Lp5_conv_block

.Lp5_conv_exit:
	v_readlane_b32 s45, v254, 15
	v_readlane_b32 s46, v255, 2
	s_nop 3
	s_lshl_b32 s45, s45, 9
	s_or_b32 s45, s45, s46
	v_mbcnt_lo_u32_b32 v0, -1, 0
	v_mbcnt_hi_u32_b32 v0, -1, v0
	v_add_u32_e32 v62, s45, v0
	s_mov_b64 s[4:5], exec
	s_branch .LBB0_884
